# hand-written pipelined weight transposer + hand-written combine phases (both layers)
# baseline (speedup 1.0000x reference)
.LBB0_799:
.LBB0_800:
	s_waitcnt vmcnt(0) lgkmcnt(0)
	s_load_dwordx2 s[0:1], s[92:93], 0x68
	v_and_b32_e32 v2, 63, v154
	v_lshlrev_b32_e32 v1, 4, v2
	v_and_b32_e32 v180, 31, v2
	v_lshlrev_b32_e32 v180, 4, v180
	v_lshlrev_b32_e32 v2, 3, v2
	v_readfirstlane_b32 s10, v154
	s_lshr_b32 s10, s10, 6
	s_lshl_b32 s12, s96, 3
	s_add_u32 s10, s10, s12
	s_lshl_b32 s12, s10, 10
	s_add_u32 s2, s90, 0x24918000
	s_addc_u32 s3, s91, 0
	s_add_u32 s2, s2, s12
	s_addc_u32 s3, s3, 0
	s_add_u32 s4, s2, 0x2000000
	s_addc_u32 s5, s3, 0
	s_lshl_b32 s12, s10, 9
	s_add_u32 s8, s90, 0x13918000
	s_addc_u32 s9, s91, 0
	s_add_u32 s8, s8, s12
	s_addc_u32 s9, s9, 0
	s_lshr_b32 s12, s10, 2
	s_mul_i32 s12, s12, 24576
	s_and_b32 s13, s10, 3
	s_lshl_b32 s13, s13, 9
	s_add_u32 s12, s12, s13
	s_add_u32 s12, s12, 8192
	s_add_u32 s6, s90, 0x15918000
	s_addc_u32 s7, s91, 0
	s_add_u32 s6, s6, s12
	s_addc_u32 s7, s7, 0
	s_waitcnt lgkmcnt(0)
	global_load_dwordx4 v[4:7], v180, s[0:1]
	global_load_dwordx4 v[12:15], v1, s[2:3]
	global_load_dwordx4 v[76:79], v1, s[4:5]
	global_load_dwordx2 v[140:141], v2, s[6:7]
	s_add_u32 s2, s2, 0x200000
	s_addc_u32 s3, s3, 0
	s_add_u32 s4, s4, 0x200000
	s_addc_u32 s5, s5, 0
	s_add_u32 s6, s6, 0xc00000
	s_addc_u32 s7, s7, 0
	global_load_dwordx4 v[16:19], v1, s[2:3]
	global_load_dwordx4 v[80:83], v1, s[4:5]
	global_load_dwordx2 v[142:143], v2, s[6:7]
	s_add_u32 s2, s2, 0x200000
	s_addc_u32 s3, s3, 0
	s_add_u32 s4, s4, 0x200000
	s_addc_u32 s5, s5, 0
	s_add_u32 s6, s6, 0xc00000
	s_addc_u32 s7, s7, 0
	global_load_dwordx4 v[20:23], v1, s[2:3]
	global_load_dwordx4 v[84:87], v1, s[4:5]
	global_load_dwordx2 v[144:145], v2, s[6:7]
	s_add_u32 s2, s2, 0x200000
	s_addc_u32 s3, s3, 0
	s_add_u32 s4, s4, 0x200000
	s_addc_u32 s5, s5, 0
	s_add_u32 s6, s6, 0xc00000
	s_addc_u32 s7, s7, 0
	global_load_dwordx4 v[24:27], v1, s[2:3]
	global_load_dwordx4 v[88:91], v1, s[4:5]
	global_load_dwordx2 v[146:147], v2, s[6:7]
	s_add_u32 s2, s2, 0x200000
	s_addc_u32 s3, s3, 0
	s_add_u32 s4, s4, 0x200000
	s_addc_u32 s5, s5, 0
	s_add_u32 s6, s6, 0xc00000
	s_addc_u32 s7, s7, 0
	global_load_dwordx4 v[28:31], v1, s[2:3]
	global_load_dwordx4 v[92:95], v1, s[4:5]
	global_load_dwordx2 v[148:149], v2, s[6:7]
	s_add_u32 s2, s2, 0x200000
	s_addc_u32 s3, s3, 0
	s_add_u32 s4, s4, 0x200000
	s_addc_u32 s5, s5, 0
	s_add_u32 s6, s6, 0xc00000
	s_addc_u32 s7, s7, 0
	global_load_dwordx4 v[32:35], v1, s[2:3]
	global_load_dwordx4 v[96:99], v1, s[4:5]
	global_load_dwordx2 v[150:151], v2, s[6:7]
	s_add_u32 s2, s2, 0x200000
	s_addc_u32 s3, s3, 0
	s_add_u32 s4, s4, 0x200000
	s_addc_u32 s5, s5, 0
	s_add_u32 s6, s6, 0xc00000
	s_addc_u32 s7, s7, 0
	global_load_dwordx4 v[36:39], v1, s[2:3]
	global_load_dwordx4 v[100:103], v1, s[4:5]
	global_load_dwordx2 v[152:153], v2, s[6:7]
	s_add_u32 s2, s2, 0x200000
	s_addc_u32 s3, s3, 0
	s_add_u32 s4, s4, 0x200000
	s_addc_u32 s5, s5, 0
	s_add_u32 s6, s6, 0xc00000
	s_addc_u32 s7, s7, 0
	global_load_dwordx4 v[40:43], v1, s[2:3]
	global_load_dwordx4 v[104:107], v1, s[4:5]
	global_load_dwordx2 v[156:157], v2, s[6:7]
	s_add_u32 s2, s2, 0x200000
	s_addc_u32 s3, s3, 0
	s_add_u32 s4, s4, 0x200000
	s_addc_u32 s5, s5, 0
	s_add_u32 s6, s6, 0xc00000
	s_addc_u32 s7, s7, 0
	global_load_dwordx4 v[44:47], v1, s[2:3]
	global_load_dwordx4 v[108:111], v1, s[4:5]
	global_load_dwordx2 v[158:159], v2, s[6:7]
	s_add_u32 s2, s2, 0x200000
	s_addc_u32 s3, s3, 0
	s_add_u32 s4, s4, 0x200000
	s_addc_u32 s5, s5, 0
	s_add_u32 s6, s6, 0xc00000
	s_addc_u32 s7, s7, 0
	global_load_dwordx4 v[48:51], v1, s[2:3]
	global_load_dwordx4 v[112:115], v1, s[4:5]
	global_load_dwordx2 v[160:161], v2, s[6:7]
	s_add_u32 s2, s2, 0x200000
	s_addc_u32 s3, s3, 0
	s_add_u32 s4, s4, 0x200000
	s_addc_u32 s5, s5, 0
	s_add_u32 s6, s6, 0xc00000
	s_addc_u32 s7, s7, 0
	global_load_dwordx4 v[52:55], v1, s[2:3]
	global_load_dwordx4 v[116:119], v1, s[4:5]
	global_load_dwordx2 v[162:163], v2, s[6:7]
	s_add_u32 s2, s2, 0x200000
	s_addc_u32 s3, s3, 0
	s_add_u32 s4, s4, 0x200000
	s_addc_u32 s5, s5, 0
	s_add_u32 s6, s6, 0xc00000
	s_addc_u32 s7, s7, 0
	global_load_dwordx4 v[56:59], v1, s[2:3]
	global_load_dwordx4 v[120:123], v1, s[4:5]
	global_load_dwordx2 v[164:165], v2, s[6:7]
	s_add_u32 s2, s2, 0x200000
	s_addc_u32 s3, s3, 0
	s_add_u32 s4, s4, 0x200000
	s_addc_u32 s5, s5, 0
	s_add_u32 s6, s6, 0xc00000
	s_addc_u32 s7, s7, 0
	global_load_dwordx4 v[60:63], v1, s[2:3]
	global_load_dwordx4 v[124:127], v1, s[4:5]
	global_load_dwordx2 v[166:167], v2, s[6:7]
	s_add_u32 s2, s2, 0x200000
	s_addc_u32 s3, s3, 0
	s_add_u32 s4, s4, 0x200000
	s_addc_u32 s5, s5, 0
	s_add_u32 s6, s6, 0xc00000
	s_addc_u32 s7, s7, 0
	global_load_dwordx4 v[64:67], v1, s[2:3]
	global_load_dwordx4 v[128:131], v1, s[4:5]
	global_load_dwordx2 v[168:169], v2, s[6:7]
	s_add_u32 s2, s2, 0x200000
	s_addc_u32 s3, s3, 0
	s_add_u32 s4, s4, 0x200000
	s_addc_u32 s5, s5, 0
	s_add_u32 s6, s6, 0xc00000
	s_addc_u32 s7, s7, 0
	global_load_dwordx4 v[68:71], v1, s[2:3]
	global_load_dwordx4 v[132:135], v1, s[4:5]
	global_load_dwordx2 v[170:171], v2, s[6:7]
	s_add_u32 s2, s2, 0x200000
	s_addc_u32 s3, s3, 0
	s_add_u32 s4, s4, 0x200000
	s_addc_u32 s5, s5, 0
	s_add_u32 s6, s6, 0xc00000
	s_addc_u32 s7, s7, 0
	global_load_dwordx4 v[72:75], v1, s[2:3]
	global_load_dwordx4 v[136:139], v1, s[4:5]
	global_load_dwordx2 v[172:173], v2, s[6:7]
	v_mov_b32_e32 v8, 0xbfb8aa3b
	v_mov_b32_e32 v9, 0xbfb8aa3b
	v_mov_b32_e32 v10, 1.0
	v_mov_b32_e32 v11, 1.0
	s_mov_b32 s20, 0x3c000000
	s_mov_b32 s21, 0x358637bd
	s_waitcnt vmcnt(45)
	v_pk_add_f32 v[12:13], v[12:13], v[76:77]
	v_pk_add_f32 v[14:15], v[14:15], v[78:79]
	v_mul_f32_e32 v180, v12, v12
	v_fmac_f32_e32 v180, v13, v13
	v_fmac_f32_e32 v180, v14, v14
	v_fmac_f32_e32 v180, v15, v15
	v_lshlrev_b32_e32 v184, 16, v140
	v_and_b32_e32 v185, 0xffff0000, v140
	v_add_f32_dpp v180, v180, v180 quad_perm:[1,0,3,2] row_mask:0xf bank_mask:0xf
	v_lshlrev_b32_e32 v186, 16, v141
	v_and_b32_e32 v187, 0xffff0000, v141
	v_add_f32_dpp v180, v180, v180 quad_perm:[2,3,0,1] row_mask:0xf bank_mask:0xf
	v_pk_mul_f32 v[188:189], v[184:185], v[8:9]
	v_pk_mul_f32 v[190:191], v[186:187], v[8:9]
	v_add_f32_dpp v180, v180, v180 row_ror:4 row_mask:0xf bank_mask:0xf
	v_exp_f32_e32 v188, v188
	v_exp_f32_e32 v189, v189
	v_add_f32_dpp v180, v180, v180 row_ror:8 row_mask:0xf bank_mask:0xf
	v_exp_f32_e32 v190, v190
	v_exp_f32_e32 v191, v191
	v_mov_b32_e32 v181, v180
	v_pk_add_f32 v[188:189], v[188:189], v[10:11]
	v_pk_add_f32 v[190:191], v[190:191], v[10:11]
	v_permlane16_swap_b32_e32 v180, v181
	v_rcp_f32_e32 v188, v188
	v_rcp_f32_e32 v189, v189
	v_add_f32_e32 v180, v180, v181
	v_rcp_f32_e32 v190, v190
	v_rcp_f32_e32 v191, v191
	v_mov_b32_e32 v182, s21
	v_fmac_f32_e32 v182, s20, v180
	v_rsq_f32_e32 v182, v182
	v_pk_mul_f32 v[188:189], v[188:189], v[184:185]
	v_pk_mul_f32 v[190:191], v[190:191], v[186:187]
	v_mov_b32_e32 v183, v182
	v_pk_mul_f32 v[188:189], v[188:189], v[4:5]
	v_pk_mul_f32 v[190:191], v[190:191], v[6:7]
	v_pk_mul_f32 v[12:13], v[12:13], v[182:183]
	v_pk_mul_f32 v[14:15], v[14:15], v[182:183]
	v_pk_mul_f32 v[12:13], v[12:13], v[188:189]
	v_pk_mul_f32 v[14:15], v[14:15], v[190:191]
	v_cvt_pk_bf16_f32 v200, v12, v13
	v_cvt_pk_bf16_f32 v201, v14, v15
	global_store_dwordx2 v2, v[200:201], s[8:9]
	s_add_u32 s8, s8, 0x100000
	s_addc_u32 s9, s9, 0
	s_waitcnt vmcnt(43)
	v_pk_add_f32 v[16:17], v[16:17], v[80:81]
	v_pk_add_f32 v[18:19], v[18:19], v[82:83]
	v_mul_f32_e32 v180, v16, v16
	v_fmac_f32_e32 v180, v17, v17
	v_fmac_f32_e32 v180, v18, v18
	v_fmac_f32_e32 v180, v19, v19
	v_lshlrev_b32_e32 v184, 16, v142
	v_and_b32_e32 v185, 0xffff0000, v142
	v_add_f32_dpp v180, v180, v180 quad_perm:[1,0,3,2] row_mask:0xf bank_mask:0xf
	v_lshlrev_b32_e32 v186, 16, v143
	v_and_b32_e32 v187, 0xffff0000, v143
	v_add_f32_dpp v180, v180, v180 quad_perm:[2,3,0,1] row_mask:0xf bank_mask:0xf
	v_pk_mul_f32 v[188:189], v[184:185], v[8:9]
	v_pk_mul_f32 v[190:191], v[186:187], v[8:9]
	v_add_f32_dpp v180, v180, v180 row_ror:4 row_mask:0xf bank_mask:0xf
	v_exp_f32_e32 v188, v188
	v_exp_f32_e32 v189, v189
	v_add_f32_dpp v180, v180, v180 row_ror:8 row_mask:0xf bank_mask:0xf
	v_exp_f32_e32 v190, v190
	v_exp_f32_e32 v191, v191
	v_mov_b32_e32 v181, v180
	v_pk_add_f32 v[188:189], v[188:189], v[10:11]
	v_pk_add_f32 v[190:191], v[190:191], v[10:11]
	v_permlane16_swap_b32_e32 v180, v181
	v_rcp_f32_e32 v188, v188
	v_rcp_f32_e32 v189, v189
	v_add_f32_e32 v180, v180, v181
	v_rcp_f32_e32 v190, v190
	v_rcp_f32_e32 v191, v191
	v_mov_b32_e32 v182, s21
	v_fmac_f32_e32 v182, s20, v180
	v_rsq_f32_e32 v182, v182
	v_pk_mul_f32 v[188:189], v[188:189], v[184:185]
	v_pk_mul_f32 v[190:191], v[190:191], v[186:187]
	v_mov_b32_e32 v183, v182
	v_pk_mul_f32 v[188:189], v[188:189], v[4:5]
	v_pk_mul_f32 v[190:191], v[190:191], v[6:7]
	v_pk_mul_f32 v[16:17], v[16:17], v[182:183]
	v_pk_mul_f32 v[18:19], v[18:19], v[182:183]
	v_pk_mul_f32 v[16:17], v[16:17], v[188:189]
	v_pk_mul_f32 v[18:19], v[18:19], v[190:191]
	v_cvt_pk_bf16_f32 v202, v16, v17
	v_cvt_pk_bf16_f32 v203, v18, v19
	global_store_dwordx2 v2, v[202:203], s[8:9]
	s_add_u32 s8, s8, 0x100000
	s_addc_u32 s9, s9, 0
	s_waitcnt vmcnt(41)
	v_pk_add_f32 v[20:21], v[20:21], v[84:85]
	v_pk_add_f32 v[22:23], v[22:23], v[86:87]
	v_mul_f32_e32 v180, v20, v20
	v_fmac_f32_e32 v180, v21, v21
	v_fmac_f32_e32 v180, v22, v22
	v_fmac_f32_e32 v180, v23, v23
	v_lshlrev_b32_e32 v184, 16, v144
	v_and_b32_e32 v185, 0xffff0000, v144
	v_add_f32_dpp v180, v180, v180 quad_perm:[1,0,3,2] row_mask:0xf bank_mask:0xf
	v_lshlrev_b32_e32 v186, 16, v145
	v_and_b32_e32 v187, 0xffff0000, v145
	v_add_f32_dpp v180, v180, v180 quad_perm:[2,3,0,1] row_mask:0xf bank_mask:0xf
	v_pk_mul_f32 v[188:189], v[184:185], v[8:9]
	v_pk_mul_f32 v[190:191], v[186:187], v[8:9]
	v_add_f32_dpp v180, v180, v180 row_ror:4 row_mask:0xf bank_mask:0xf
	v_exp_f32_e32 v188, v188
	v_exp_f32_e32 v189, v189
	v_add_f32_dpp v180, v180, v180 row_ror:8 row_mask:0xf bank_mask:0xf
	v_exp_f32_e32 v190, v190
	v_exp_f32_e32 v191, v191
	v_mov_b32_e32 v181, v180
	v_pk_add_f32 v[188:189], v[188:189], v[10:11]
	v_pk_add_f32 v[190:191], v[190:191], v[10:11]
	v_permlane16_swap_b32_e32 v180, v181
	v_rcp_f32_e32 v188, v188
	v_rcp_f32_e32 v189, v189
	v_add_f32_e32 v180, v180, v181
	v_rcp_f32_e32 v190, v190
	v_rcp_f32_e32 v191, v191
	v_mov_b32_e32 v182, s21
	v_fmac_f32_e32 v182, s20, v180
	v_rsq_f32_e32 v182, v182
	v_pk_mul_f32 v[188:189], v[188:189], v[184:185]
	v_pk_mul_f32 v[190:191], v[190:191], v[186:187]
	v_mov_b32_e32 v183, v182
	v_pk_mul_f32 v[188:189], v[188:189], v[4:5]
	v_pk_mul_f32 v[190:191], v[190:191], v[6:7]
	v_pk_mul_f32 v[20:21], v[20:21], v[182:183]
	v_pk_mul_f32 v[22:23], v[22:23], v[182:183]
	v_pk_mul_f32 v[20:21], v[20:21], v[188:189]
	v_pk_mul_f32 v[22:23], v[22:23], v[190:191]
	v_cvt_pk_bf16_f32 v204, v20, v21
	v_cvt_pk_bf16_f32 v205, v22, v23
	global_store_dwordx2 v2, v[204:205], s[8:9]
	s_add_u32 s8, s8, 0x100000
	s_addc_u32 s9, s9, 0
	s_waitcnt vmcnt(39)
	v_pk_add_f32 v[24:25], v[24:25], v[88:89]
	v_pk_add_f32 v[26:27], v[26:27], v[90:91]
	v_mul_f32_e32 v180, v24, v24
	v_fmac_f32_e32 v180, v25, v25
	v_fmac_f32_e32 v180, v26, v26
	v_fmac_f32_e32 v180, v27, v27
	v_lshlrev_b32_e32 v184, 16, v146
	v_and_b32_e32 v185, 0xffff0000, v146
	v_add_f32_dpp v180, v180, v180 quad_perm:[1,0,3,2] row_mask:0xf bank_mask:0xf
	v_lshlrev_b32_e32 v186, 16, v147
	v_and_b32_e32 v187, 0xffff0000, v147
	v_add_f32_dpp v180, v180, v180 quad_perm:[2,3,0,1] row_mask:0xf bank_mask:0xf
	v_pk_mul_f32 v[188:189], v[184:185], v[8:9]
	v_pk_mul_f32 v[190:191], v[186:187], v[8:9]
	v_add_f32_dpp v180, v180, v180 row_ror:4 row_mask:0xf bank_mask:0xf
	v_exp_f32_e32 v188, v188
	v_exp_f32_e32 v189, v189
	v_add_f32_dpp v180, v180, v180 row_ror:8 row_mask:0xf bank_mask:0xf
	v_exp_f32_e32 v190, v190
	v_exp_f32_e32 v191, v191
	v_mov_b32_e32 v181, v180
	v_pk_add_f32 v[188:189], v[188:189], v[10:11]
	v_pk_add_f32 v[190:191], v[190:191], v[10:11]
	v_permlane16_swap_b32_e32 v180, v181
	v_rcp_f32_e32 v188, v188
	v_rcp_f32_e32 v189, v189
	v_add_f32_e32 v180, v180, v181
	v_rcp_f32_e32 v190, v190
	v_rcp_f32_e32 v191, v191
	v_mov_b32_e32 v182, s21
	v_fmac_f32_e32 v182, s20, v180
	v_rsq_f32_e32 v182, v182
	v_pk_mul_f32 v[188:189], v[188:189], v[184:185]
	v_pk_mul_f32 v[190:191], v[190:191], v[186:187]
	v_mov_b32_e32 v183, v182
	v_pk_mul_f32 v[188:189], v[188:189], v[4:5]
	v_pk_mul_f32 v[190:191], v[190:191], v[6:7]
	v_pk_mul_f32 v[24:25], v[24:25], v[182:183]
	v_pk_mul_f32 v[26:27], v[26:27], v[182:183]
	v_pk_mul_f32 v[24:25], v[24:25], v[188:189]
	v_pk_mul_f32 v[26:27], v[26:27], v[190:191]
	v_cvt_pk_bf16_f32 v206, v24, v25
	v_cvt_pk_bf16_f32 v207, v26, v27
	global_store_dwordx2 v2, v[206:207], s[8:9]
	s_add_u32 s8, s8, 0x100000
	s_addc_u32 s9, s9, 0
	s_waitcnt vmcnt(37)
	v_pk_add_f32 v[28:29], v[28:29], v[92:93]
	v_pk_add_f32 v[30:31], v[30:31], v[94:95]
	v_mul_f32_e32 v180, v28, v28
	v_fmac_f32_e32 v180, v29, v29
	v_fmac_f32_e32 v180, v30, v30
	v_fmac_f32_e32 v180, v31, v31
	v_lshlrev_b32_e32 v184, 16, v148
	v_and_b32_e32 v185, 0xffff0000, v148
	v_add_f32_dpp v180, v180, v180 quad_perm:[1,0,3,2] row_mask:0xf bank_mask:0xf
	v_lshlrev_b32_e32 v186, 16, v149
	v_and_b32_e32 v187, 0xffff0000, v149
	v_add_f32_dpp v180, v180, v180 quad_perm:[2,3,0,1] row_mask:0xf bank_mask:0xf
	v_pk_mul_f32 v[188:189], v[184:185], v[8:9]
	v_pk_mul_f32 v[190:191], v[186:187], v[8:9]
	v_add_f32_dpp v180, v180, v180 row_ror:4 row_mask:0xf bank_mask:0xf
	v_exp_f32_e32 v188, v188
	v_exp_f32_e32 v189, v189
	v_add_f32_dpp v180, v180, v180 row_ror:8 row_mask:0xf bank_mask:0xf
	v_exp_f32_e32 v190, v190
	v_exp_f32_e32 v191, v191
	v_mov_b32_e32 v181, v180
	v_pk_add_f32 v[188:189], v[188:189], v[10:11]
	v_pk_add_f32 v[190:191], v[190:191], v[10:11]
	v_permlane16_swap_b32_e32 v180, v181
	v_rcp_f32_e32 v188, v188
	v_rcp_f32_e32 v189, v189
	v_add_f32_e32 v180, v180, v181
	v_rcp_f32_e32 v190, v190
	v_rcp_f32_e32 v191, v191
	v_mov_b32_e32 v182, s21
	v_fmac_f32_e32 v182, s20, v180
	v_rsq_f32_e32 v182, v182
	v_pk_mul_f32 v[188:189], v[188:189], v[184:185]
	v_pk_mul_f32 v[190:191], v[190:191], v[186:187]
	v_mov_b32_e32 v183, v182
	v_pk_mul_f32 v[188:189], v[188:189], v[4:5]
	v_pk_mul_f32 v[190:191], v[190:191], v[6:7]
	v_pk_mul_f32 v[28:29], v[28:29], v[182:183]
	v_pk_mul_f32 v[30:31], v[30:31], v[182:183]
	v_pk_mul_f32 v[28:29], v[28:29], v[188:189]
	v_pk_mul_f32 v[30:31], v[30:31], v[190:191]
	v_cvt_pk_bf16_f32 v200, v28, v29
	v_cvt_pk_bf16_f32 v201, v30, v31
	global_store_dwordx2 v2, v[200:201], s[8:9]
	s_add_u32 s8, s8, 0x100000
	s_addc_u32 s9, s9, 0
	s_waitcnt vmcnt(35)
	v_pk_add_f32 v[32:33], v[32:33], v[96:97]
	v_pk_add_f32 v[34:35], v[34:35], v[98:99]
	v_mul_f32_e32 v180, v32, v32
	v_fmac_f32_e32 v180, v33, v33
	v_fmac_f32_e32 v180, v34, v34
	v_fmac_f32_e32 v180, v35, v35
	v_lshlrev_b32_e32 v184, 16, v150
	v_and_b32_e32 v185, 0xffff0000, v150
	v_add_f32_dpp v180, v180, v180 quad_perm:[1,0,3,2] row_mask:0xf bank_mask:0xf
	v_lshlrev_b32_e32 v186, 16, v151
	v_and_b32_e32 v187, 0xffff0000, v151
	v_add_f32_dpp v180, v180, v180 quad_perm:[2,3,0,1] row_mask:0xf bank_mask:0xf
	v_pk_mul_f32 v[188:189], v[184:185], v[8:9]
	v_pk_mul_f32 v[190:191], v[186:187], v[8:9]
	v_add_f32_dpp v180, v180, v180 row_ror:4 row_mask:0xf bank_mask:0xf
	v_exp_f32_e32 v188, v188
	v_exp_f32_e32 v189, v189
	v_add_f32_dpp v180, v180, v180 row_ror:8 row_mask:0xf bank_mask:0xf
	v_exp_f32_e32 v190, v190
	v_exp_f32_e32 v191, v191
	v_mov_b32_e32 v181, v180
	v_pk_add_f32 v[188:189], v[188:189], v[10:11]
	v_pk_add_f32 v[190:191], v[190:191], v[10:11]
	v_permlane16_swap_b32_e32 v180, v181
	v_rcp_f32_e32 v188, v188
	v_rcp_f32_e32 v189, v189
	v_add_f32_e32 v180, v180, v181
	v_rcp_f32_e32 v190, v190
	v_rcp_f32_e32 v191, v191
	v_mov_b32_e32 v182, s21
	v_fmac_f32_e32 v182, s20, v180
	v_rsq_f32_e32 v182, v182
	v_pk_mul_f32 v[188:189], v[188:189], v[184:185]
	v_pk_mul_f32 v[190:191], v[190:191], v[186:187]
	v_mov_b32_e32 v183, v182
	v_pk_mul_f32 v[188:189], v[188:189], v[4:5]
	v_pk_mul_f32 v[190:191], v[190:191], v[6:7]
	v_pk_mul_f32 v[32:33], v[32:33], v[182:183]
	v_pk_mul_f32 v[34:35], v[34:35], v[182:183]
	v_pk_mul_f32 v[32:33], v[32:33], v[188:189]
	v_pk_mul_f32 v[34:35], v[34:35], v[190:191]
	v_cvt_pk_bf16_f32 v202, v32, v33
	v_cvt_pk_bf16_f32 v203, v34, v35
	global_store_dwordx2 v2, v[202:203], s[8:9]
	s_add_u32 s8, s8, 0x100000
	s_addc_u32 s9, s9, 0
	s_waitcnt vmcnt(33)
	v_pk_add_f32 v[36:37], v[36:37], v[100:101]
	v_pk_add_f32 v[38:39], v[38:39], v[102:103]
	v_mul_f32_e32 v180, v36, v36
	v_fmac_f32_e32 v180, v37, v37
	v_fmac_f32_e32 v180, v38, v38
	v_fmac_f32_e32 v180, v39, v39
	v_lshlrev_b32_e32 v184, 16, v152
	v_and_b32_e32 v185, 0xffff0000, v152
	v_add_f32_dpp v180, v180, v180 quad_perm:[1,0,3,2] row_mask:0xf bank_mask:0xf
	v_lshlrev_b32_e32 v186, 16, v153
	v_and_b32_e32 v187, 0xffff0000, v153
	v_add_f32_dpp v180, v180, v180 quad_perm:[2,3,0,1] row_mask:0xf bank_mask:0xf
	v_pk_mul_f32 v[188:189], v[184:185], v[8:9]
	v_pk_mul_f32 v[190:191], v[186:187], v[8:9]
	v_add_f32_dpp v180, v180, v180 row_ror:4 row_mask:0xf bank_mask:0xf
	v_exp_f32_e32 v188, v188
	v_exp_f32_e32 v189, v189
	v_add_f32_dpp v180, v180, v180 row_ror:8 row_mask:0xf bank_mask:0xf
	v_exp_f32_e32 v190, v190
	v_exp_f32_e32 v191, v191
	v_mov_b32_e32 v181, v180
	v_pk_add_f32 v[188:189], v[188:189], v[10:11]
	v_pk_add_f32 v[190:191], v[190:191], v[10:11]
	v_permlane16_swap_b32_e32 v180, v181
	v_rcp_f32_e32 v188, v188
	v_rcp_f32_e32 v189, v189
	v_add_f32_e32 v180, v180, v181
	v_rcp_f32_e32 v190, v190
	v_rcp_f32_e32 v191, v191
	v_mov_b32_e32 v182, s21
	v_fmac_f32_e32 v182, s20, v180
	v_rsq_f32_e32 v182, v182
	v_pk_mul_f32 v[188:189], v[188:189], v[184:185]
	v_pk_mul_f32 v[190:191], v[190:191], v[186:187]
	v_mov_b32_e32 v183, v182
	v_pk_mul_f32 v[188:189], v[188:189], v[4:5]
	v_pk_mul_f32 v[190:191], v[190:191], v[6:7]
	v_pk_mul_f32 v[36:37], v[36:37], v[182:183]
	v_pk_mul_f32 v[38:39], v[38:39], v[182:183]
	v_pk_mul_f32 v[36:37], v[36:37], v[188:189]
	v_pk_mul_f32 v[38:39], v[38:39], v[190:191]
	v_cvt_pk_bf16_f32 v204, v36, v37
	v_cvt_pk_bf16_f32 v205, v38, v39
	global_store_dwordx2 v2, v[204:205], s[8:9]
	s_add_u32 s8, s8, 0x100000
	s_addc_u32 s9, s9, 0
	s_waitcnt vmcnt(31)
	v_pk_add_f32 v[40:41], v[40:41], v[104:105]
	v_pk_add_f32 v[42:43], v[42:43], v[106:107]
	v_mul_f32_e32 v180, v40, v40
	v_fmac_f32_e32 v180, v41, v41
	v_fmac_f32_e32 v180, v42, v42
	v_fmac_f32_e32 v180, v43, v43
	v_lshlrev_b32_e32 v184, 16, v156
	v_and_b32_e32 v185, 0xffff0000, v156
	v_add_f32_dpp v180, v180, v180 quad_perm:[1,0,3,2] row_mask:0xf bank_mask:0xf
	v_lshlrev_b32_e32 v186, 16, v157
	v_and_b32_e32 v187, 0xffff0000, v157
	v_add_f32_dpp v180, v180, v180 quad_perm:[2,3,0,1] row_mask:0xf bank_mask:0xf
	v_pk_mul_f32 v[188:189], v[184:185], v[8:9]
	v_pk_mul_f32 v[190:191], v[186:187], v[8:9]
	v_add_f32_dpp v180, v180, v180 row_ror:4 row_mask:0xf bank_mask:0xf
	v_exp_f32_e32 v188, v188
	v_exp_f32_e32 v189, v189
	v_add_f32_dpp v180, v180, v180 row_ror:8 row_mask:0xf bank_mask:0xf
	v_exp_f32_e32 v190, v190
	v_exp_f32_e32 v191, v191
	v_mov_b32_e32 v181, v180
	v_pk_add_f32 v[188:189], v[188:189], v[10:11]
	v_pk_add_f32 v[190:191], v[190:191], v[10:11]
	v_permlane16_swap_b32_e32 v180, v181
	v_rcp_f32_e32 v188, v188
	v_rcp_f32_e32 v189, v189
	v_add_f32_e32 v180, v180, v181
	v_rcp_f32_e32 v190, v190
	v_rcp_f32_e32 v191, v191
	v_mov_b32_e32 v182, s21
	v_fmac_f32_e32 v182, s20, v180
	v_rsq_f32_e32 v182, v182
	v_pk_mul_f32 v[188:189], v[188:189], v[184:185]
	v_pk_mul_f32 v[190:191], v[190:191], v[186:187]
	v_mov_b32_e32 v183, v182
	v_pk_mul_f32 v[188:189], v[188:189], v[4:5]
	v_pk_mul_f32 v[190:191], v[190:191], v[6:7]
	v_pk_mul_f32 v[40:41], v[40:41], v[182:183]
	v_pk_mul_f32 v[42:43], v[42:43], v[182:183]
	v_pk_mul_f32 v[40:41], v[40:41], v[188:189]
	v_pk_mul_f32 v[42:43], v[42:43], v[190:191]
	v_cvt_pk_bf16_f32 v206, v40, v41
	v_cvt_pk_bf16_f32 v207, v42, v43
	global_store_dwordx2 v2, v[206:207], s[8:9]
	s_add_u32 s8, s8, 0x100000
	s_addc_u32 s9, s9, 0
	s_waitcnt vmcnt(29)
	v_pk_add_f32 v[44:45], v[44:45], v[108:109]
	v_pk_add_f32 v[46:47], v[46:47], v[110:111]
	v_mul_f32_e32 v180, v44, v44
	v_fmac_f32_e32 v180, v45, v45
	v_fmac_f32_e32 v180, v46, v46
	v_fmac_f32_e32 v180, v47, v47
	v_lshlrev_b32_e32 v184, 16, v158
	v_and_b32_e32 v185, 0xffff0000, v158
	v_add_f32_dpp v180, v180, v180 quad_perm:[1,0,3,2] row_mask:0xf bank_mask:0xf
	v_lshlrev_b32_e32 v186, 16, v159
	v_and_b32_e32 v187, 0xffff0000, v159
	v_add_f32_dpp v180, v180, v180 quad_perm:[2,3,0,1] row_mask:0xf bank_mask:0xf
	v_pk_mul_f32 v[188:189], v[184:185], v[8:9]
	v_pk_mul_f32 v[190:191], v[186:187], v[8:9]
	v_add_f32_dpp v180, v180, v180 row_ror:4 row_mask:0xf bank_mask:0xf
	v_exp_f32_e32 v188, v188
	v_exp_f32_e32 v189, v189
	v_add_f32_dpp v180, v180, v180 row_ror:8 row_mask:0xf bank_mask:0xf
	v_exp_f32_e32 v190, v190
	v_exp_f32_e32 v191, v191
	v_mov_b32_e32 v181, v180
	v_pk_add_f32 v[188:189], v[188:189], v[10:11]
	v_pk_add_f32 v[190:191], v[190:191], v[10:11]
	v_permlane16_swap_b32_e32 v180, v181
	v_rcp_f32_e32 v188, v188
	v_rcp_f32_e32 v189, v189
	v_add_f32_e32 v180, v180, v181
	v_rcp_f32_e32 v190, v190
	v_rcp_f32_e32 v191, v191
	v_mov_b32_e32 v182, s21
	v_fmac_f32_e32 v182, s20, v180
	v_rsq_f32_e32 v182, v182
	v_pk_mul_f32 v[188:189], v[188:189], v[184:185]
	v_pk_mul_f32 v[190:191], v[190:191], v[186:187]
	v_mov_b32_e32 v183, v182
	v_pk_mul_f32 v[188:189], v[188:189], v[4:5]
	v_pk_mul_f32 v[190:191], v[190:191], v[6:7]
	v_pk_mul_f32 v[44:45], v[44:45], v[182:183]
	v_pk_mul_f32 v[46:47], v[46:47], v[182:183]
	v_pk_mul_f32 v[44:45], v[44:45], v[188:189]
	v_pk_mul_f32 v[46:47], v[46:47], v[190:191]
	v_cvt_pk_bf16_f32 v200, v44, v45
	v_cvt_pk_bf16_f32 v201, v46, v47
	global_store_dwordx2 v2, v[200:201], s[8:9]
	s_add_u32 s8, s8, 0x100000
	s_addc_u32 s9, s9, 0
	s_waitcnt vmcnt(27)
	v_pk_add_f32 v[48:49], v[48:49], v[112:113]
	v_pk_add_f32 v[50:51], v[50:51], v[114:115]
	v_mul_f32_e32 v180, v48, v48
	v_fmac_f32_e32 v180, v49, v49
	v_fmac_f32_e32 v180, v50, v50
	v_fmac_f32_e32 v180, v51, v51
	v_lshlrev_b32_e32 v184, 16, v160
	v_and_b32_e32 v185, 0xffff0000, v160
	v_add_f32_dpp v180, v180, v180 quad_perm:[1,0,3,2] row_mask:0xf bank_mask:0xf
	v_lshlrev_b32_e32 v186, 16, v161
	v_and_b32_e32 v187, 0xffff0000, v161
	v_add_f32_dpp v180, v180, v180 quad_perm:[2,3,0,1] row_mask:0xf bank_mask:0xf
	v_pk_mul_f32 v[188:189], v[184:185], v[8:9]
	v_pk_mul_f32 v[190:191], v[186:187], v[8:9]
	v_add_f32_dpp v180, v180, v180 row_ror:4 row_mask:0xf bank_mask:0xf
	v_exp_f32_e32 v188, v188
	v_exp_f32_e32 v189, v189
	v_add_f32_dpp v180, v180, v180 row_ror:8 row_mask:0xf bank_mask:0xf
	v_exp_f32_e32 v190, v190
	v_exp_f32_e32 v191, v191
	v_mov_b32_e32 v181, v180
	v_pk_add_f32 v[188:189], v[188:189], v[10:11]
	v_pk_add_f32 v[190:191], v[190:191], v[10:11]
	v_permlane16_swap_b32_e32 v180, v181
	v_rcp_f32_e32 v188, v188
	v_rcp_f32_e32 v189, v189
	v_add_f32_e32 v180, v180, v181
	v_rcp_f32_e32 v190, v190
	v_rcp_f32_e32 v191, v191
	v_mov_b32_e32 v182, s21
	v_fmac_f32_e32 v182, s20, v180
	v_rsq_f32_e32 v182, v182
	v_pk_mul_f32 v[188:189], v[188:189], v[184:185]
	v_pk_mul_f32 v[190:191], v[190:191], v[186:187]
	v_mov_b32_e32 v183, v182
	v_pk_mul_f32 v[188:189], v[188:189], v[4:5]
	v_pk_mul_f32 v[190:191], v[190:191], v[6:7]
	v_pk_mul_f32 v[48:49], v[48:49], v[182:183]
	v_pk_mul_f32 v[50:51], v[50:51], v[182:183]
	v_pk_mul_f32 v[48:49], v[48:49], v[188:189]
	v_pk_mul_f32 v[50:51], v[50:51], v[190:191]
	v_cvt_pk_bf16_f32 v202, v48, v49
	v_cvt_pk_bf16_f32 v203, v50, v51
	global_store_dwordx2 v2, v[202:203], s[8:9]
	s_add_u32 s8, s8, 0x100000
	s_addc_u32 s9, s9, 0
	s_waitcnt vmcnt(25)
	v_pk_add_f32 v[52:53], v[52:53], v[116:117]
	v_pk_add_f32 v[54:55], v[54:55], v[118:119]
	v_mul_f32_e32 v180, v52, v52
	v_fmac_f32_e32 v180, v53, v53
	v_fmac_f32_e32 v180, v54, v54
	v_fmac_f32_e32 v180, v55, v55
	v_lshlrev_b32_e32 v184, 16, v162
	v_and_b32_e32 v185, 0xffff0000, v162
	v_add_f32_dpp v180, v180, v180 quad_perm:[1,0,3,2] row_mask:0xf bank_mask:0xf
	v_lshlrev_b32_e32 v186, 16, v163
	v_and_b32_e32 v187, 0xffff0000, v163
	v_add_f32_dpp v180, v180, v180 quad_perm:[2,3,0,1] row_mask:0xf bank_mask:0xf
	v_pk_mul_f32 v[188:189], v[184:185], v[8:9]
	v_pk_mul_f32 v[190:191], v[186:187], v[8:9]
	v_add_f32_dpp v180, v180, v180 row_ror:4 row_mask:0xf bank_mask:0xf
	v_exp_f32_e32 v188, v188
	v_exp_f32_e32 v189, v189
	v_add_f32_dpp v180, v180, v180 row_ror:8 row_mask:0xf bank_mask:0xf
	v_exp_f32_e32 v190, v190
	v_exp_f32_e32 v191, v191
	v_mov_b32_e32 v181, v180
	v_pk_add_f32 v[188:189], v[188:189], v[10:11]
	v_pk_add_f32 v[190:191], v[190:191], v[10:11]
	v_permlane16_swap_b32_e32 v180, v181
	v_rcp_f32_e32 v188, v188
	v_rcp_f32_e32 v189, v189
	v_add_f32_e32 v180, v180, v181
	v_rcp_f32_e32 v190, v190
	v_rcp_f32_e32 v191, v191
	v_mov_b32_e32 v182, s21
	v_fmac_f32_e32 v182, s20, v180
	v_rsq_f32_e32 v182, v182
	v_pk_mul_f32 v[188:189], v[188:189], v[184:185]
	v_pk_mul_f32 v[190:191], v[190:191], v[186:187]
	v_mov_b32_e32 v183, v182
	v_pk_mul_f32 v[188:189], v[188:189], v[4:5]
	v_pk_mul_f32 v[190:191], v[190:191], v[6:7]
	v_pk_mul_f32 v[52:53], v[52:53], v[182:183]
	v_pk_mul_f32 v[54:55], v[54:55], v[182:183]
	v_pk_mul_f32 v[52:53], v[52:53], v[188:189]
	v_pk_mul_f32 v[54:55], v[54:55], v[190:191]
	v_cvt_pk_bf16_f32 v204, v52, v53
	v_cvt_pk_bf16_f32 v205, v54, v55
	global_store_dwordx2 v2, v[204:205], s[8:9]
	s_add_u32 s8, s8, 0x100000
	s_addc_u32 s9, s9, 0
	s_waitcnt vmcnt(23)
	v_pk_add_f32 v[56:57], v[56:57], v[120:121]
	v_pk_add_f32 v[58:59], v[58:59], v[122:123]
	v_mul_f32_e32 v180, v56, v56
	v_fmac_f32_e32 v180, v57, v57
	v_fmac_f32_e32 v180, v58, v58
	v_fmac_f32_e32 v180, v59, v59
	v_lshlrev_b32_e32 v184, 16, v164
	v_and_b32_e32 v185, 0xffff0000, v164
	v_add_f32_dpp v180, v180, v180 quad_perm:[1,0,3,2] row_mask:0xf bank_mask:0xf
	v_lshlrev_b32_e32 v186, 16, v165
	v_and_b32_e32 v187, 0xffff0000, v165
	v_add_f32_dpp v180, v180, v180 quad_perm:[2,3,0,1] row_mask:0xf bank_mask:0xf
	v_pk_mul_f32 v[188:189], v[184:185], v[8:9]
	v_pk_mul_f32 v[190:191], v[186:187], v[8:9]
	v_add_f32_dpp v180, v180, v180 row_ror:4 row_mask:0xf bank_mask:0xf
	v_exp_f32_e32 v188, v188
	v_exp_f32_e32 v189, v189
	v_add_f32_dpp v180, v180, v180 row_ror:8 row_mask:0xf bank_mask:0xf
	v_exp_f32_e32 v190, v190
	v_exp_f32_e32 v191, v191
	v_mov_b32_e32 v181, v180
	v_pk_add_f32 v[188:189], v[188:189], v[10:11]
	v_pk_add_f32 v[190:191], v[190:191], v[10:11]
	v_permlane16_swap_b32_e32 v180, v181
	v_rcp_f32_e32 v188, v188
	v_rcp_f32_e32 v189, v189
	v_add_f32_e32 v180, v180, v181
	v_rcp_f32_e32 v190, v190
	v_rcp_f32_e32 v191, v191
	v_mov_b32_e32 v182, s21
	v_fmac_f32_e32 v182, s20, v180
	v_rsq_f32_e32 v182, v182
	v_pk_mul_f32 v[188:189], v[188:189], v[184:185]
	v_pk_mul_f32 v[190:191], v[190:191], v[186:187]
	v_mov_b32_e32 v183, v182
	v_pk_mul_f32 v[188:189], v[188:189], v[4:5]
	v_pk_mul_f32 v[190:191], v[190:191], v[6:7]
	v_pk_mul_f32 v[56:57], v[56:57], v[182:183]
	v_pk_mul_f32 v[58:59], v[58:59], v[182:183]
	v_pk_mul_f32 v[56:57], v[56:57], v[188:189]
	v_pk_mul_f32 v[58:59], v[58:59], v[190:191]
	v_cvt_pk_bf16_f32 v206, v56, v57
	v_cvt_pk_bf16_f32 v207, v58, v59
	global_store_dwordx2 v2, v[206:207], s[8:9]
	s_add_u32 s8, s8, 0x100000
	s_addc_u32 s9, s9, 0
	s_waitcnt vmcnt(21)
	v_pk_add_f32 v[60:61], v[60:61], v[124:125]
	v_pk_add_f32 v[62:63], v[62:63], v[126:127]
	v_mul_f32_e32 v180, v60, v60
	v_fmac_f32_e32 v180, v61, v61
	v_fmac_f32_e32 v180, v62, v62
	v_fmac_f32_e32 v180, v63, v63
	v_lshlrev_b32_e32 v184, 16, v166
	v_and_b32_e32 v185, 0xffff0000, v166
	v_add_f32_dpp v180, v180, v180 quad_perm:[1,0,3,2] row_mask:0xf bank_mask:0xf
	v_lshlrev_b32_e32 v186, 16, v167
	v_and_b32_e32 v187, 0xffff0000, v167
	v_add_f32_dpp v180, v180, v180 quad_perm:[2,3,0,1] row_mask:0xf bank_mask:0xf
	v_pk_mul_f32 v[188:189], v[184:185], v[8:9]
	v_pk_mul_f32 v[190:191], v[186:187], v[8:9]
	v_add_f32_dpp v180, v180, v180 row_ror:4 row_mask:0xf bank_mask:0xf
	v_exp_f32_e32 v188, v188
	v_exp_f32_e32 v189, v189
	v_add_f32_dpp v180, v180, v180 row_ror:8 row_mask:0xf bank_mask:0xf
	v_exp_f32_e32 v190, v190
	v_exp_f32_e32 v191, v191
	v_mov_b32_e32 v181, v180
	v_pk_add_f32 v[188:189], v[188:189], v[10:11]
	v_pk_add_f32 v[190:191], v[190:191], v[10:11]
	v_permlane16_swap_b32_e32 v180, v181
	v_rcp_f32_e32 v188, v188
	v_rcp_f32_e32 v189, v189
	v_add_f32_e32 v180, v180, v181
	v_rcp_f32_e32 v190, v190
	v_rcp_f32_e32 v191, v191
	v_mov_b32_e32 v182, s21
	v_fmac_f32_e32 v182, s20, v180
	v_rsq_f32_e32 v182, v182
	v_pk_mul_f32 v[188:189], v[188:189], v[184:185]
	v_pk_mul_f32 v[190:191], v[190:191], v[186:187]
	v_mov_b32_e32 v183, v182
	v_pk_mul_f32 v[188:189], v[188:189], v[4:5]
	v_pk_mul_f32 v[190:191], v[190:191], v[6:7]
	v_pk_mul_f32 v[60:61], v[60:61], v[182:183]
	v_pk_mul_f32 v[62:63], v[62:63], v[182:183]
	v_pk_mul_f32 v[60:61], v[60:61], v[188:189]
	v_pk_mul_f32 v[62:63], v[62:63], v[190:191]
	v_cvt_pk_bf16_f32 v200, v60, v61
	v_cvt_pk_bf16_f32 v201, v62, v63
	global_store_dwordx2 v2, v[200:201], s[8:9]
	s_add_u32 s8, s8, 0x100000
	s_addc_u32 s9, s9, 0
	s_waitcnt vmcnt(19)
	v_pk_add_f32 v[64:65], v[64:65], v[128:129]
	v_pk_add_f32 v[66:67], v[66:67], v[130:131]
	v_mul_f32_e32 v180, v64, v64
	v_fmac_f32_e32 v180, v65, v65
	v_fmac_f32_e32 v180, v66, v66
	v_fmac_f32_e32 v180, v67, v67
	v_lshlrev_b32_e32 v184, 16, v168
	v_and_b32_e32 v185, 0xffff0000, v168
	v_add_f32_dpp v180, v180, v180 quad_perm:[1,0,3,2] row_mask:0xf bank_mask:0xf
	v_lshlrev_b32_e32 v186, 16, v169
	v_and_b32_e32 v187, 0xffff0000, v169
	v_add_f32_dpp v180, v180, v180 quad_perm:[2,3,0,1] row_mask:0xf bank_mask:0xf
	v_pk_mul_f32 v[188:189], v[184:185], v[8:9]
	v_pk_mul_f32 v[190:191], v[186:187], v[8:9]
	v_add_f32_dpp v180, v180, v180 row_ror:4 row_mask:0xf bank_mask:0xf
	v_exp_f32_e32 v188, v188
	v_exp_f32_e32 v189, v189
	v_add_f32_dpp v180, v180, v180 row_ror:8 row_mask:0xf bank_mask:0xf
	v_exp_f32_e32 v190, v190
	v_exp_f32_e32 v191, v191
	v_mov_b32_e32 v181, v180
	v_pk_add_f32 v[188:189], v[188:189], v[10:11]
	v_pk_add_f32 v[190:191], v[190:191], v[10:11]
	v_permlane16_swap_b32_e32 v180, v181
	v_rcp_f32_e32 v188, v188
	v_rcp_f32_e32 v189, v189
	v_add_f32_e32 v180, v180, v181
	v_rcp_f32_e32 v190, v190
	v_rcp_f32_e32 v191, v191
	v_mov_b32_e32 v182, s21
	v_fmac_f32_e32 v182, s20, v180
	v_rsq_f32_e32 v182, v182
	v_pk_mul_f32 v[188:189], v[188:189], v[184:185]
	v_pk_mul_f32 v[190:191], v[190:191], v[186:187]
	v_mov_b32_e32 v183, v182
	v_pk_mul_f32 v[188:189], v[188:189], v[4:5]
	v_pk_mul_f32 v[190:191], v[190:191], v[6:7]
	v_pk_mul_f32 v[64:65], v[64:65], v[182:183]
	v_pk_mul_f32 v[66:67], v[66:67], v[182:183]
	v_pk_mul_f32 v[64:65], v[64:65], v[188:189]
	v_pk_mul_f32 v[66:67], v[66:67], v[190:191]
	v_cvt_pk_bf16_f32 v202, v64, v65
	v_cvt_pk_bf16_f32 v203, v66, v67
	global_store_dwordx2 v2, v[202:203], s[8:9]
	s_add_u32 s8, s8, 0x100000
	s_addc_u32 s9, s9, 0
	s_waitcnt vmcnt(17)
	v_pk_add_f32 v[68:69], v[68:69], v[132:133]
	v_pk_add_f32 v[70:71], v[70:71], v[134:135]
	v_mul_f32_e32 v180, v68, v68
	v_fmac_f32_e32 v180, v69, v69
	v_fmac_f32_e32 v180, v70, v70
	v_fmac_f32_e32 v180, v71, v71
	v_lshlrev_b32_e32 v184, 16, v170
	v_and_b32_e32 v185, 0xffff0000, v170
	v_add_f32_dpp v180, v180, v180 quad_perm:[1,0,3,2] row_mask:0xf bank_mask:0xf
	v_lshlrev_b32_e32 v186, 16, v171
	v_and_b32_e32 v187, 0xffff0000, v171
	v_add_f32_dpp v180, v180, v180 quad_perm:[2,3,0,1] row_mask:0xf bank_mask:0xf
	v_pk_mul_f32 v[188:189], v[184:185], v[8:9]
	v_pk_mul_f32 v[190:191], v[186:187], v[8:9]
	v_add_f32_dpp v180, v180, v180 row_ror:4 row_mask:0xf bank_mask:0xf
	v_exp_f32_e32 v188, v188
	v_exp_f32_e32 v189, v189
	v_add_f32_dpp v180, v180, v180 row_ror:8 row_mask:0xf bank_mask:0xf
	v_exp_f32_e32 v190, v190
	v_exp_f32_e32 v191, v191
	v_mov_b32_e32 v181, v180
	v_pk_add_f32 v[188:189], v[188:189], v[10:11]
	v_pk_add_f32 v[190:191], v[190:191], v[10:11]
	v_permlane16_swap_b32_e32 v180, v181
	v_rcp_f32_e32 v188, v188
	v_rcp_f32_e32 v189, v189
	v_add_f32_e32 v180, v180, v181
	v_rcp_f32_e32 v190, v190
	v_rcp_f32_e32 v191, v191
	v_mov_b32_e32 v182, s21
	v_fmac_f32_e32 v182, s20, v180
	v_rsq_f32_e32 v182, v182
	v_pk_mul_f32 v[188:189], v[188:189], v[184:185]
	v_pk_mul_f32 v[190:191], v[190:191], v[186:187]
	v_mov_b32_e32 v183, v182
	v_pk_mul_f32 v[188:189], v[188:189], v[4:5]
	v_pk_mul_f32 v[190:191], v[190:191], v[6:7]
	v_pk_mul_f32 v[68:69], v[68:69], v[182:183]
	v_pk_mul_f32 v[70:71], v[70:71], v[182:183]
	v_pk_mul_f32 v[68:69], v[68:69], v[188:189]
	v_pk_mul_f32 v[70:71], v[70:71], v[190:191]
	v_cvt_pk_bf16_f32 v204, v68, v69
	v_cvt_pk_bf16_f32 v205, v70, v71
	global_store_dwordx2 v2, v[204:205], s[8:9]
	s_add_u32 s8, s8, 0x100000
	s_addc_u32 s9, s9, 0
	s_waitcnt vmcnt(15)
	v_pk_add_f32 v[72:73], v[72:73], v[136:137]
	v_pk_add_f32 v[74:75], v[74:75], v[138:139]
	v_mul_f32_e32 v180, v72, v72
	v_fmac_f32_e32 v180, v73, v73
	v_fmac_f32_e32 v180, v74, v74
	v_fmac_f32_e32 v180, v75, v75
	v_lshlrev_b32_e32 v184, 16, v172
	v_and_b32_e32 v185, 0xffff0000, v172
	v_add_f32_dpp v180, v180, v180 quad_perm:[1,0,3,2] row_mask:0xf bank_mask:0xf
	v_lshlrev_b32_e32 v186, 16, v173
	v_and_b32_e32 v187, 0xffff0000, v173
	v_add_f32_dpp v180, v180, v180 quad_perm:[2,3,0,1] row_mask:0xf bank_mask:0xf
	v_pk_mul_f32 v[188:189], v[184:185], v[8:9]
	v_pk_mul_f32 v[190:191], v[186:187], v[8:9]
	v_add_f32_dpp v180, v180, v180 row_ror:4 row_mask:0xf bank_mask:0xf
	v_exp_f32_e32 v188, v188
	v_exp_f32_e32 v189, v189
	v_add_f32_dpp v180, v180, v180 row_ror:8 row_mask:0xf bank_mask:0xf
	v_exp_f32_e32 v190, v190
	v_exp_f32_e32 v191, v191
	v_mov_b32_e32 v181, v180
	v_pk_add_f32 v[188:189], v[188:189], v[10:11]
	v_pk_add_f32 v[190:191], v[190:191], v[10:11]
	v_permlane16_swap_b32_e32 v180, v181
	v_rcp_f32_e32 v188, v188
	v_rcp_f32_e32 v189, v189
	v_add_f32_e32 v180, v180, v181
	v_rcp_f32_e32 v190, v190
	v_rcp_f32_e32 v191, v191
	v_mov_b32_e32 v182, s21
	v_fmac_f32_e32 v182, s20, v180
	v_rsq_f32_e32 v182, v182
	v_pk_mul_f32 v[188:189], v[188:189], v[184:185]
	v_pk_mul_f32 v[190:191], v[190:191], v[186:187]
	v_mov_b32_e32 v183, v182
	v_pk_mul_f32 v[188:189], v[188:189], v[4:5]
	v_pk_mul_f32 v[190:191], v[190:191], v[6:7]
	v_pk_mul_f32 v[72:73], v[72:73], v[182:183]
	v_pk_mul_f32 v[74:75], v[74:75], v[182:183]
	v_pk_mul_f32 v[72:73], v[72:73], v[188:189]
	v_pk_mul_f32 v[74:75], v[74:75], v[190:191]
	v_cvt_pk_bf16_f32 v206, v72, v73
	v_cvt_pk_bf16_f32 v207, v74, v75
	global_store_dwordx2 v2, v[206:207], s[8:9]
	s_waitcnt vmcnt(0)
	s_branch .LBB0_804

.LBB0_2040:
.LBB0_2041:
	s_waitcnt vmcnt(0) lgkmcnt(0)
	s_load_dwordx2 s[0:1], s[92:93], 0x68
	v_and_b32_e32 v2, 63, v154
	v_lshlrev_b32_e32 v1, 4, v2
	v_and_b32_e32 v180, 31, v2
	v_lshlrev_b32_e32 v180, 4, v180
	v_lshlrev_b32_e32 v2, 3, v2
	v_readfirstlane_b32 s10, v154
	s_lshr_b32 s10, s10, 6
	s_lshl_b32 s12, s96, 3
	s_add_u32 s10, s10, s12
	s_lshl_b32 s12, s10, 10
	s_add_u32 s2, s90, 0x24918000
	s_addc_u32 s3, s91, 0
	s_add_u32 s2, s2, s12
	s_addc_u32 s3, s3, 0
	s_add_u32 s4, s2, 0x2000000
	s_addc_u32 s5, s3, 0
	s_lshl_b32 s12, s10, 9
	s_add_u32 s8, s90, 0x13918000
	s_addc_u32 s9, s91, 0
	s_add_u32 s8, s8, s12
	s_addc_u32 s9, s9, 0
	s_lshr_b32 s12, s10, 2
	s_mul_i32 s12, s12, 24576
	s_and_b32 s13, s10, 3
	s_lshl_b32 s13, s13, 9
	s_add_u32 s12, s12, s13
	s_add_u32 s12, s12, 8192
	s_add_u32 s6, s90, 0x15918000
	s_addc_u32 s7, s91, 0
	s_add_u32 s6, s6, s12
	s_addc_u32 s7, s7, 0
	s_waitcnt lgkmcnt(0)
	s_add_u32 s0, s0, 512
	s_addc_u32 s1, s1, 0
	global_load_dwordx4 v[4:7], v180, s[0:1]
	global_load_dwordx4 v[12:15], v1, s[2:3]
	global_load_dwordx4 v[76:79], v1, s[4:5]
	global_load_dwordx2 v[140:141], v2, s[6:7]
	s_add_u32 s2, s2, 0x200000
	s_addc_u32 s3, s3, 0
	s_add_u32 s4, s4, 0x200000
	s_addc_u32 s5, s5, 0
	s_add_u32 s6, s6, 0xc00000
	s_addc_u32 s7, s7, 0
	global_load_dwordx4 v[16:19], v1, s[2:3]
	global_load_dwordx4 v[80:83], v1, s[4:5]
	global_load_dwordx2 v[142:143], v2, s[6:7]
	s_add_u32 s2, s2, 0x200000
	s_addc_u32 s3, s3, 0
	s_add_u32 s4, s4, 0x200000
	s_addc_u32 s5, s5, 0
	s_add_u32 s6, s6, 0xc00000
	s_addc_u32 s7, s7, 0
	global_load_dwordx4 v[20:23], v1, s[2:3]
	global_load_dwordx4 v[84:87], v1, s[4:5]
	global_load_dwordx2 v[144:145], v2, s[6:7]
	s_add_u32 s2, s2, 0x200000
	s_addc_u32 s3, s3, 0
	s_add_u32 s4, s4, 0x200000
	s_addc_u32 s5, s5, 0
	s_add_u32 s6, s6, 0xc00000
	s_addc_u32 s7, s7, 0
	global_load_dwordx4 v[24:27], v1, s[2:3]
	global_load_dwordx4 v[88:91], v1, s[4:5]
	global_load_dwordx2 v[146:147], v2, s[6:7]
	s_add_u32 s2, s2, 0x200000
	s_addc_u32 s3, s3, 0
	s_add_u32 s4, s4, 0x200000
	s_addc_u32 s5, s5, 0
	s_add_u32 s6, s6, 0xc00000
	s_addc_u32 s7, s7, 0
	global_load_dwordx4 v[28:31], v1, s[2:3]
	global_load_dwordx4 v[92:95], v1, s[4:5]
	global_load_dwordx2 v[148:149], v2, s[6:7]
	s_add_u32 s2, s2, 0x200000
	s_addc_u32 s3, s3, 0
	s_add_u32 s4, s4, 0x200000
	s_addc_u32 s5, s5, 0
	s_add_u32 s6, s6, 0xc00000
	s_addc_u32 s7, s7, 0
	global_load_dwordx4 v[32:35], v1, s[2:3]
	global_load_dwordx4 v[96:99], v1, s[4:5]
	global_load_dwordx2 v[150:151], v2, s[6:7]
	s_add_u32 s2, s2, 0x200000
	s_addc_u32 s3, s3, 0
	s_add_u32 s4, s4, 0x200000
	s_addc_u32 s5, s5, 0
	s_add_u32 s6, s6, 0xc00000
	s_addc_u32 s7, s7, 0
	global_load_dwordx4 v[36:39], v1, s[2:3]
	global_load_dwordx4 v[100:103], v1, s[4:5]
	global_load_dwordx2 v[152:153], v2, s[6:7]
	s_add_u32 s2, s2, 0x200000
	s_addc_u32 s3, s3, 0
	s_add_u32 s4, s4, 0x200000
	s_addc_u32 s5, s5, 0
	s_add_u32 s6, s6, 0xc00000
	s_addc_u32 s7, s7, 0
	global_load_dwordx4 v[40:43], v1, s[2:3]
	global_load_dwordx4 v[104:107], v1, s[4:5]
	global_load_dwordx2 v[156:157], v2, s[6:7]
	s_add_u32 s2, s2, 0x200000
	s_addc_u32 s3, s3, 0
	s_add_u32 s4, s4, 0x200000
	s_addc_u32 s5, s5, 0
	s_add_u32 s6, s6, 0xc00000
	s_addc_u32 s7, s7, 0
	global_load_dwordx4 v[44:47], v1, s[2:3]
	global_load_dwordx4 v[108:111], v1, s[4:5]
	global_load_dwordx2 v[158:159], v2, s[6:7]
	s_add_u32 s2, s2, 0x200000
	s_addc_u32 s3, s3, 0
	s_add_u32 s4, s4, 0x200000
	s_addc_u32 s5, s5, 0
	s_add_u32 s6, s6, 0xc00000
	s_addc_u32 s7, s7, 0
	global_load_dwordx4 v[48:51], v1, s[2:3]
	global_load_dwordx4 v[112:115], v1, s[4:5]
	global_load_dwordx2 v[160:161], v2, s[6:7]
	s_add_u32 s2, s2, 0x200000
	s_addc_u32 s3, s3, 0
	s_add_u32 s4, s4, 0x200000
	s_addc_u32 s5, s5, 0
	s_add_u32 s6, s6, 0xc00000
	s_addc_u32 s7, s7, 0
	global_load_dwordx4 v[52:55], v1, s[2:3]
	global_load_dwordx4 v[116:119], v1, s[4:5]
	global_load_dwordx2 v[162:163], v2, s[6:7]
	s_add_u32 s2, s2, 0x200000
	s_addc_u32 s3, s3, 0
	s_add_u32 s4, s4, 0x200000
	s_addc_u32 s5, s5, 0
	s_add_u32 s6, s6, 0xc00000
	s_addc_u32 s7, s7, 0
	global_load_dwordx4 v[56:59], v1, s[2:3]
	global_load_dwordx4 v[120:123], v1, s[4:5]
	global_load_dwordx2 v[164:165], v2, s[6:7]
	s_add_u32 s2, s2, 0x200000
	s_addc_u32 s3, s3, 0
	s_add_u32 s4, s4, 0x200000
	s_addc_u32 s5, s5, 0
	s_add_u32 s6, s6, 0xc00000
	s_addc_u32 s7, s7, 0
	global_load_dwordx4 v[60:63], v1, s[2:3]
	global_load_dwordx4 v[124:127], v1, s[4:5]
	global_load_dwordx2 v[166:167], v2, s[6:7]
	s_add_u32 s2, s2, 0x200000
	s_addc_u32 s3, s3, 0
	s_add_u32 s4, s4, 0x200000
	s_addc_u32 s5, s5, 0
	s_add_u32 s6, s6, 0xc00000
	s_addc_u32 s7, s7, 0
	global_load_dwordx4 v[64:67], v1, s[2:3]
	global_load_dwordx4 v[128:131], v1, s[4:5]
	global_load_dwordx2 v[168:169], v2, s[6:7]
	s_add_u32 s2, s2, 0x200000
	s_addc_u32 s3, s3, 0
	s_add_u32 s4, s4, 0x200000
	s_addc_u32 s5, s5, 0
	s_add_u32 s6, s6, 0xc00000
	s_addc_u32 s7, s7, 0
	global_load_dwordx4 v[68:71], v1, s[2:3]
	global_load_dwordx4 v[132:135], v1, s[4:5]
	global_load_dwordx2 v[170:171], v2, s[6:7]
	s_add_u32 s2, s2, 0x200000
	s_addc_u32 s3, s3, 0
	s_add_u32 s4, s4, 0x200000
	s_addc_u32 s5, s5, 0
	s_add_u32 s6, s6, 0xc00000
	s_addc_u32 s7, s7, 0
	global_load_dwordx4 v[72:75], v1, s[2:3]
	global_load_dwordx4 v[136:139], v1, s[4:5]
	global_load_dwordx2 v[172:173], v2, s[6:7]
	v_mov_b32_e32 v8, 0xbfb8aa3b
	v_mov_b32_e32 v9, 0xbfb8aa3b
	v_mov_b32_e32 v10, 1.0
	v_mov_b32_e32 v11, 1.0
	s_mov_b32 s20, 0x3c000000
	s_mov_b32 s21, 0x358637bd
	s_waitcnt vmcnt(45)
	v_pk_add_f32 v[12:13], v[12:13], v[76:77]
	v_pk_add_f32 v[14:15], v[14:15], v[78:79]
	v_mul_f32_e32 v180, v12, v12
	v_fmac_f32_e32 v180, v13, v13
	v_fmac_f32_e32 v180, v14, v14
	v_fmac_f32_e32 v180, v15, v15
	v_lshlrev_b32_e32 v184, 16, v140
	v_and_b32_e32 v185, 0xffff0000, v140
	v_add_f32_dpp v180, v180, v180 quad_perm:[1,0,3,2] row_mask:0xf bank_mask:0xf
	v_lshlrev_b32_e32 v186, 16, v141
	v_and_b32_e32 v187, 0xffff0000, v141
	v_add_f32_dpp v180, v180, v180 quad_perm:[2,3,0,1] row_mask:0xf bank_mask:0xf
	v_pk_mul_f32 v[188:189], v[184:185], v[8:9]
	v_pk_mul_f32 v[190:191], v[186:187], v[8:9]
	v_add_f32_dpp v180, v180, v180 row_ror:4 row_mask:0xf bank_mask:0xf
	v_exp_f32_e32 v188, v188
	v_exp_f32_e32 v189, v189
	v_add_f32_dpp v180, v180, v180 row_ror:8 row_mask:0xf bank_mask:0xf
	v_exp_f32_e32 v190, v190
	v_exp_f32_e32 v191, v191
	v_mov_b32_e32 v181, v180
	v_pk_add_f32 v[188:189], v[188:189], v[10:11]
	v_pk_add_f32 v[190:191], v[190:191], v[10:11]
	v_permlane16_swap_b32_e32 v180, v181
	v_rcp_f32_e32 v188, v188
	v_rcp_f32_e32 v189, v189
	v_add_f32_e32 v180, v180, v181
	v_rcp_f32_e32 v190, v190
	v_rcp_f32_e32 v191, v191
	v_mov_b32_e32 v182, s21
	v_fmac_f32_e32 v182, s20, v180
	v_rsq_f32_e32 v182, v182
	v_pk_mul_f32 v[188:189], v[188:189], v[184:185]
	v_pk_mul_f32 v[190:191], v[190:191], v[186:187]
	v_mov_b32_e32 v183, v182
	v_pk_mul_f32 v[188:189], v[188:189], v[4:5]
	v_pk_mul_f32 v[190:191], v[190:191], v[6:7]
	v_pk_mul_f32 v[12:13], v[12:13], v[182:183]
	v_pk_mul_f32 v[14:15], v[14:15], v[182:183]
	v_pk_mul_f32 v[12:13], v[12:13], v[188:189]
	v_pk_mul_f32 v[14:15], v[14:15], v[190:191]
	v_cvt_pk_bf16_f32 v200, v12, v13
	v_cvt_pk_bf16_f32 v201, v14, v15
	global_store_dwordx2 v2, v[200:201], s[8:9]
	s_add_u32 s8, s8, 0x100000
	s_addc_u32 s9, s9, 0
	s_waitcnt vmcnt(43)
	v_pk_add_f32 v[16:17], v[16:17], v[80:81]
	v_pk_add_f32 v[18:19], v[18:19], v[82:83]
	v_mul_f32_e32 v180, v16, v16
	v_fmac_f32_e32 v180, v17, v17
	v_fmac_f32_e32 v180, v18, v18
	v_fmac_f32_e32 v180, v19, v19
	v_lshlrev_b32_e32 v184, 16, v142
	v_and_b32_e32 v185, 0xffff0000, v142
	v_add_f32_dpp v180, v180, v180 quad_perm:[1,0,3,2] row_mask:0xf bank_mask:0xf
	v_lshlrev_b32_e32 v186, 16, v143
	v_and_b32_e32 v187, 0xffff0000, v143
	v_add_f32_dpp v180, v180, v180 quad_perm:[2,3,0,1] row_mask:0xf bank_mask:0xf
	v_pk_mul_f32 v[188:189], v[184:185], v[8:9]
	v_pk_mul_f32 v[190:191], v[186:187], v[8:9]
	v_add_f32_dpp v180, v180, v180 row_ror:4 row_mask:0xf bank_mask:0xf
	v_exp_f32_e32 v188, v188
	v_exp_f32_e32 v189, v189
	v_add_f32_dpp v180, v180, v180 row_ror:8 row_mask:0xf bank_mask:0xf
	v_exp_f32_e32 v190, v190
	v_exp_f32_e32 v191, v191
	v_mov_b32_e32 v181, v180
	v_pk_add_f32 v[188:189], v[188:189], v[10:11]
	v_pk_add_f32 v[190:191], v[190:191], v[10:11]
	v_permlane16_swap_b32_e32 v180, v181
	v_rcp_f32_e32 v188, v188
	v_rcp_f32_e32 v189, v189
	v_add_f32_e32 v180, v180, v181
	v_rcp_f32_e32 v190, v190
	v_rcp_f32_e32 v191, v191
	v_mov_b32_e32 v182, s21
	v_fmac_f32_e32 v182, s20, v180
	v_rsq_f32_e32 v182, v182
	v_pk_mul_f32 v[188:189], v[188:189], v[184:185]
	v_pk_mul_f32 v[190:191], v[190:191], v[186:187]
	v_mov_b32_e32 v183, v182
	v_pk_mul_f32 v[188:189], v[188:189], v[4:5]
	v_pk_mul_f32 v[190:191], v[190:191], v[6:7]
	v_pk_mul_f32 v[16:17], v[16:17], v[182:183]
	v_pk_mul_f32 v[18:19], v[18:19], v[182:183]
	v_pk_mul_f32 v[16:17], v[16:17], v[188:189]
	v_pk_mul_f32 v[18:19], v[18:19], v[190:191]
	v_cvt_pk_bf16_f32 v202, v16, v17
	v_cvt_pk_bf16_f32 v203, v18, v19
	global_store_dwordx2 v2, v[202:203], s[8:9]
	s_add_u32 s8, s8, 0x100000
	s_addc_u32 s9, s9, 0
	s_waitcnt vmcnt(41)
	v_pk_add_f32 v[20:21], v[20:21], v[84:85]
	v_pk_add_f32 v[22:23], v[22:23], v[86:87]
	v_mul_f32_e32 v180, v20, v20
	v_fmac_f32_e32 v180, v21, v21
	v_fmac_f32_e32 v180, v22, v22
	v_fmac_f32_e32 v180, v23, v23
	v_lshlrev_b32_e32 v184, 16, v144
	v_and_b32_e32 v185, 0xffff0000, v144
	v_add_f32_dpp v180, v180, v180 quad_perm:[1,0,3,2] row_mask:0xf bank_mask:0xf
	v_lshlrev_b32_e32 v186, 16, v145
	v_and_b32_e32 v187, 0xffff0000, v145
	v_add_f32_dpp v180, v180, v180 quad_perm:[2,3,0,1] row_mask:0xf bank_mask:0xf
	v_pk_mul_f32 v[188:189], v[184:185], v[8:9]
	v_pk_mul_f32 v[190:191], v[186:187], v[8:9]
	v_add_f32_dpp v180, v180, v180 row_ror:4 row_mask:0xf bank_mask:0xf
	v_exp_f32_e32 v188, v188
	v_exp_f32_e32 v189, v189
	v_add_f32_dpp v180, v180, v180 row_ror:8 row_mask:0xf bank_mask:0xf
	v_exp_f32_e32 v190, v190
	v_exp_f32_e32 v191, v191
	v_mov_b32_e32 v181, v180
	v_pk_add_f32 v[188:189], v[188:189], v[10:11]
	v_pk_add_f32 v[190:191], v[190:191], v[10:11]
	v_permlane16_swap_b32_e32 v180, v181
	v_rcp_f32_e32 v188, v188
	v_rcp_f32_e32 v189, v189
	v_add_f32_e32 v180, v180, v181
	v_rcp_f32_e32 v190, v190
	v_rcp_f32_e32 v191, v191
	v_mov_b32_e32 v182, s21
	v_fmac_f32_e32 v182, s20, v180
	v_rsq_f32_e32 v182, v182
	v_pk_mul_f32 v[188:189], v[188:189], v[184:185]
	v_pk_mul_f32 v[190:191], v[190:191], v[186:187]
	v_mov_b32_e32 v183, v182
	v_pk_mul_f32 v[188:189], v[188:189], v[4:5]
	v_pk_mul_f32 v[190:191], v[190:191], v[6:7]
	v_pk_mul_f32 v[20:21], v[20:21], v[182:183]
	v_pk_mul_f32 v[22:23], v[22:23], v[182:183]
	v_pk_mul_f32 v[20:21], v[20:21], v[188:189]
	v_pk_mul_f32 v[22:23], v[22:23], v[190:191]
	v_cvt_pk_bf16_f32 v204, v20, v21
	v_cvt_pk_bf16_f32 v205, v22, v23
	global_store_dwordx2 v2, v[204:205], s[8:9]
	s_add_u32 s8, s8, 0x100000
	s_addc_u32 s9, s9, 0
	s_waitcnt vmcnt(39)
	v_pk_add_f32 v[24:25], v[24:25], v[88:89]
	v_pk_add_f32 v[26:27], v[26:27], v[90:91]
	v_mul_f32_e32 v180, v24, v24
	v_fmac_f32_e32 v180, v25, v25
	v_fmac_f32_e32 v180, v26, v26
	v_fmac_f32_e32 v180, v27, v27
	v_lshlrev_b32_e32 v184, 16, v146
	v_and_b32_e32 v185, 0xffff0000, v146
	v_add_f32_dpp v180, v180, v180 quad_perm:[1,0,3,2] row_mask:0xf bank_mask:0xf
	v_lshlrev_b32_e32 v186, 16, v147
	v_and_b32_e32 v187, 0xffff0000, v147
	v_add_f32_dpp v180, v180, v180 quad_perm:[2,3,0,1] row_mask:0xf bank_mask:0xf
	v_pk_mul_f32 v[188:189], v[184:185], v[8:9]
	v_pk_mul_f32 v[190:191], v[186:187], v[8:9]
	v_add_f32_dpp v180, v180, v180 row_ror:4 row_mask:0xf bank_mask:0xf
	v_exp_f32_e32 v188, v188
	v_exp_f32_e32 v189, v189
	v_add_f32_dpp v180, v180, v180 row_ror:8 row_mask:0xf bank_mask:0xf
	v_exp_f32_e32 v190, v190
	v_exp_f32_e32 v191, v191
	v_mov_b32_e32 v181, v180
	v_pk_add_f32 v[188:189], v[188:189], v[10:11]
	v_pk_add_f32 v[190:191], v[190:191], v[10:11]
	v_permlane16_swap_b32_e32 v180, v181
	v_rcp_f32_e32 v188, v188
	v_rcp_f32_e32 v189, v189
	v_add_f32_e32 v180, v180, v181
	v_rcp_f32_e32 v190, v190
	v_rcp_f32_e32 v191, v191
	v_mov_b32_e32 v182, s21
	v_fmac_f32_e32 v182, s20, v180
	v_rsq_f32_e32 v182, v182
	v_pk_mul_f32 v[188:189], v[188:189], v[184:185]
	v_pk_mul_f32 v[190:191], v[190:191], v[186:187]
	v_mov_b32_e32 v183, v182
	v_pk_mul_f32 v[188:189], v[188:189], v[4:5]
	v_pk_mul_f32 v[190:191], v[190:191], v[6:7]
	v_pk_mul_f32 v[24:25], v[24:25], v[182:183]
	v_pk_mul_f32 v[26:27], v[26:27], v[182:183]
	v_pk_mul_f32 v[24:25], v[24:25], v[188:189]
	v_pk_mul_f32 v[26:27], v[26:27], v[190:191]
	v_cvt_pk_bf16_f32 v206, v24, v25
	v_cvt_pk_bf16_f32 v207, v26, v27
	global_store_dwordx2 v2, v[206:207], s[8:9]
	s_add_u32 s8, s8, 0x100000
	s_addc_u32 s9, s9, 0
	s_waitcnt vmcnt(37)
	v_pk_add_f32 v[28:29], v[28:29], v[92:93]
	v_pk_add_f32 v[30:31], v[30:31], v[94:95]
	v_mul_f32_e32 v180, v28, v28
	v_fmac_f32_e32 v180, v29, v29
	v_fmac_f32_e32 v180, v30, v30
	v_fmac_f32_e32 v180, v31, v31
	v_lshlrev_b32_e32 v184, 16, v148
	v_and_b32_e32 v185, 0xffff0000, v148
	v_add_f32_dpp v180, v180, v180 quad_perm:[1,0,3,2] row_mask:0xf bank_mask:0xf
	v_lshlrev_b32_e32 v186, 16, v149
	v_and_b32_e32 v187, 0xffff0000, v149
	v_add_f32_dpp v180, v180, v180 quad_perm:[2,3,0,1] row_mask:0xf bank_mask:0xf
	v_pk_mul_f32 v[188:189], v[184:185], v[8:9]
	v_pk_mul_f32 v[190:191], v[186:187], v[8:9]
	v_add_f32_dpp v180, v180, v180 row_ror:4 row_mask:0xf bank_mask:0xf
	v_exp_f32_e32 v188, v188
	v_exp_f32_e32 v189, v189
	v_add_f32_dpp v180, v180, v180 row_ror:8 row_mask:0xf bank_mask:0xf
	v_exp_f32_e32 v190, v190
	v_exp_f32_e32 v191, v191
	v_mov_b32_e32 v181, v180
	v_pk_add_f32 v[188:189], v[188:189], v[10:11]
	v_pk_add_f32 v[190:191], v[190:191], v[10:11]
	v_permlane16_swap_b32_e32 v180, v181
	v_rcp_f32_e32 v188, v188
	v_rcp_f32_e32 v189, v189
	v_add_f32_e32 v180, v180, v181
	v_rcp_f32_e32 v190, v190
	v_rcp_f32_e32 v191, v191
	v_mov_b32_e32 v182, s21
	v_fmac_f32_e32 v182, s20, v180
	v_rsq_f32_e32 v182, v182
	v_pk_mul_f32 v[188:189], v[188:189], v[184:185]
	v_pk_mul_f32 v[190:191], v[190:191], v[186:187]
	v_mov_b32_e32 v183, v182
	v_pk_mul_f32 v[188:189], v[188:189], v[4:5]
	v_pk_mul_f32 v[190:191], v[190:191], v[6:7]
	v_pk_mul_f32 v[28:29], v[28:29], v[182:183]
	v_pk_mul_f32 v[30:31], v[30:31], v[182:183]
	v_pk_mul_f32 v[28:29], v[28:29], v[188:189]
	v_pk_mul_f32 v[30:31], v[30:31], v[190:191]
	v_cvt_pk_bf16_f32 v200, v28, v29
	v_cvt_pk_bf16_f32 v201, v30, v31
	global_store_dwordx2 v2, v[200:201], s[8:9]
	s_add_u32 s8, s8, 0x100000
	s_addc_u32 s9, s9, 0
	s_waitcnt vmcnt(35)
	v_pk_add_f32 v[32:33], v[32:33], v[96:97]
	v_pk_add_f32 v[34:35], v[34:35], v[98:99]
	v_mul_f32_e32 v180, v32, v32
	v_fmac_f32_e32 v180, v33, v33
	v_fmac_f32_e32 v180, v34, v34
	v_fmac_f32_e32 v180, v35, v35
	v_lshlrev_b32_e32 v184, 16, v150
	v_and_b32_e32 v185, 0xffff0000, v150
	v_add_f32_dpp v180, v180, v180 quad_perm:[1,0,3,2] row_mask:0xf bank_mask:0xf
	v_lshlrev_b32_e32 v186, 16, v151
	v_and_b32_e32 v187, 0xffff0000, v151
	v_add_f32_dpp v180, v180, v180 quad_perm:[2,3,0,1] row_mask:0xf bank_mask:0xf
	v_pk_mul_f32 v[188:189], v[184:185], v[8:9]
	v_pk_mul_f32 v[190:191], v[186:187], v[8:9]
	v_add_f32_dpp v180, v180, v180 row_ror:4 row_mask:0xf bank_mask:0xf
	v_exp_f32_e32 v188, v188
	v_exp_f32_e32 v189, v189
	v_add_f32_dpp v180, v180, v180 row_ror:8 row_mask:0xf bank_mask:0xf
	v_exp_f32_e32 v190, v190
	v_exp_f32_e32 v191, v191
	v_mov_b32_e32 v181, v180
	v_pk_add_f32 v[188:189], v[188:189], v[10:11]
	v_pk_add_f32 v[190:191], v[190:191], v[10:11]
	v_permlane16_swap_b32_e32 v180, v181
	v_rcp_f32_e32 v188, v188
	v_rcp_f32_e32 v189, v189
	v_add_f32_e32 v180, v180, v181
	v_rcp_f32_e32 v190, v190
	v_rcp_f32_e32 v191, v191
	v_mov_b32_e32 v182, s21
	v_fmac_f32_e32 v182, s20, v180
	v_rsq_f32_e32 v182, v182
	v_pk_mul_f32 v[188:189], v[188:189], v[184:185]
	v_pk_mul_f32 v[190:191], v[190:191], v[186:187]
	v_mov_b32_e32 v183, v182
	v_pk_mul_f32 v[188:189], v[188:189], v[4:5]
	v_pk_mul_f32 v[190:191], v[190:191], v[6:7]
	v_pk_mul_f32 v[32:33], v[32:33], v[182:183]
	v_pk_mul_f32 v[34:35], v[34:35], v[182:183]
	v_pk_mul_f32 v[32:33], v[32:33], v[188:189]
	v_pk_mul_f32 v[34:35], v[34:35], v[190:191]
	v_cvt_pk_bf16_f32 v202, v32, v33
	v_cvt_pk_bf16_f32 v203, v34, v35
	global_store_dwordx2 v2, v[202:203], s[8:9]
	s_add_u32 s8, s8, 0x100000
	s_addc_u32 s9, s9, 0
	s_waitcnt vmcnt(33)
	v_pk_add_f32 v[36:37], v[36:37], v[100:101]
	v_pk_add_f32 v[38:39], v[38:39], v[102:103]
	v_mul_f32_e32 v180, v36, v36
	v_fmac_f32_e32 v180, v37, v37
	v_fmac_f32_e32 v180, v38, v38
	v_fmac_f32_e32 v180, v39, v39
	v_lshlrev_b32_e32 v184, 16, v152
	v_and_b32_e32 v185, 0xffff0000, v152
	v_add_f32_dpp v180, v180, v180 quad_perm:[1,0,3,2] row_mask:0xf bank_mask:0xf
	v_lshlrev_b32_e32 v186, 16, v153
	v_and_b32_e32 v187, 0xffff0000, v153
	v_add_f32_dpp v180, v180, v180 quad_perm:[2,3,0,1] row_mask:0xf bank_mask:0xf
	v_pk_mul_f32 v[188:189], v[184:185], v[8:9]
	v_pk_mul_f32 v[190:191], v[186:187], v[8:9]
	v_add_f32_dpp v180, v180, v180 row_ror:4 row_mask:0xf bank_mask:0xf
	v_exp_f32_e32 v188, v188
	v_exp_f32_e32 v189, v189
	v_add_f32_dpp v180, v180, v180 row_ror:8 row_mask:0xf bank_mask:0xf
	v_exp_f32_e32 v190, v190
	v_exp_f32_e32 v191, v191
	v_mov_b32_e32 v181, v180
	v_pk_add_f32 v[188:189], v[188:189], v[10:11]
	v_pk_add_f32 v[190:191], v[190:191], v[10:11]
	v_permlane16_swap_b32_e32 v180, v181
	v_rcp_f32_e32 v188, v188
	v_rcp_f32_e32 v189, v189
	v_add_f32_e32 v180, v180, v181
	v_rcp_f32_e32 v190, v190
	v_rcp_f32_e32 v191, v191
	v_mov_b32_e32 v182, s21
	v_fmac_f32_e32 v182, s20, v180
	v_rsq_f32_e32 v182, v182
	v_pk_mul_f32 v[188:189], v[188:189], v[184:185]
	v_pk_mul_f32 v[190:191], v[190:191], v[186:187]
	v_mov_b32_e32 v183, v182
	v_pk_mul_f32 v[188:189], v[188:189], v[4:5]
	v_pk_mul_f32 v[190:191], v[190:191], v[6:7]
	v_pk_mul_f32 v[36:37], v[36:37], v[182:183]
	v_pk_mul_f32 v[38:39], v[38:39], v[182:183]
	v_pk_mul_f32 v[36:37], v[36:37], v[188:189]
	v_pk_mul_f32 v[38:39], v[38:39], v[190:191]
	v_cvt_pk_bf16_f32 v204, v36, v37
	v_cvt_pk_bf16_f32 v205, v38, v39
	global_store_dwordx2 v2, v[204:205], s[8:9]
	s_add_u32 s8, s8, 0x100000
	s_addc_u32 s9, s9, 0
	s_waitcnt vmcnt(31)
	v_pk_add_f32 v[40:41], v[40:41], v[104:105]
	v_pk_add_f32 v[42:43], v[42:43], v[106:107]
	v_mul_f32_e32 v180, v40, v40
	v_fmac_f32_e32 v180, v41, v41
	v_fmac_f32_e32 v180, v42, v42
	v_fmac_f32_e32 v180, v43, v43
	v_lshlrev_b32_e32 v184, 16, v156
	v_and_b32_e32 v185, 0xffff0000, v156
	v_add_f32_dpp v180, v180, v180 quad_perm:[1,0,3,2] row_mask:0xf bank_mask:0xf
	v_lshlrev_b32_e32 v186, 16, v157
	v_and_b32_e32 v187, 0xffff0000, v157
	v_add_f32_dpp v180, v180, v180 quad_perm:[2,3,0,1] row_mask:0xf bank_mask:0xf
	v_pk_mul_f32 v[188:189], v[184:185], v[8:9]
	v_pk_mul_f32 v[190:191], v[186:187], v[8:9]
	v_add_f32_dpp v180, v180, v180 row_ror:4 row_mask:0xf bank_mask:0xf
	v_exp_f32_e32 v188, v188
	v_exp_f32_e32 v189, v189
	v_add_f32_dpp v180, v180, v180 row_ror:8 row_mask:0xf bank_mask:0xf
	v_exp_f32_e32 v190, v190
	v_exp_f32_e32 v191, v191
	v_mov_b32_e32 v181, v180
	v_pk_add_f32 v[188:189], v[188:189], v[10:11]
	v_pk_add_f32 v[190:191], v[190:191], v[10:11]
	v_permlane16_swap_b32_e32 v180, v181
	v_rcp_f32_e32 v188, v188
	v_rcp_f32_e32 v189, v189
	v_add_f32_e32 v180, v180, v181
	v_rcp_f32_e32 v190, v190
	v_rcp_f32_e32 v191, v191
	v_mov_b32_e32 v182, s21
	v_fmac_f32_e32 v182, s20, v180
	v_rsq_f32_e32 v182, v182
	v_pk_mul_f32 v[188:189], v[188:189], v[184:185]
	v_pk_mul_f32 v[190:191], v[190:191], v[186:187]
	v_mov_b32_e32 v183, v182
	v_pk_mul_f32 v[188:189], v[188:189], v[4:5]
	v_pk_mul_f32 v[190:191], v[190:191], v[6:7]
	v_pk_mul_f32 v[40:41], v[40:41], v[182:183]
	v_pk_mul_f32 v[42:43], v[42:43], v[182:183]
	v_pk_mul_f32 v[40:41], v[40:41], v[188:189]
	v_pk_mul_f32 v[42:43], v[42:43], v[190:191]
	v_cvt_pk_bf16_f32 v206, v40, v41
	v_cvt_pk_bf16_f32 v207, v42, v43
	global_store_dwordx2 v2, v[206:207], s[8:9]
	s_add_u32 s8, s8, 0x100000
	s_addc_u32 s9, s9, 0
	s_waitcnt vmcnt(29)
	v_pk_add_f32 v[44:45], v[44:45], v[108:109]
	v_pk_add_f32 v[46:47], v[46:47], v[110:111]
	v_mul_f32_e32 v180, v44, v44
	v_fmac_f32_e32 v180, v45, v45
	v_fmac_f32_e32 v180, v46, v46
	v_fmac_f32_e32 v180, v47, v47
	v_lshlrev_b32_e32 v184, 16, v158
	v_and_b32_e32 v185, 0xffff0000, v158
	v_add_f32_dpp v180, v180, v180 quad_perm:[1,0,3,2] row_mask:0xf bank_mask:0xf
	v_lshlrev_b32_e32 v186, 16, v159
	v_and_b32_e32 v187, 0xffff0000, v159
	v_add_f32_dpp v180, v180, v180 quad_perm:[2,3,0,1] row_mask:0xf bank_mask:0xf
	v_pk_mul_f32 v[188:189], v[184:185], v[8:9]
	v_pk_mul_f32 v[190:191], v[186:187], v[8:9]
	v_add_f32_dpp v180, v180, v180 row_ror:4 row_mask:0xf bank_mask:0xf
	v_exp_f32_e32 v188, v188
	v_exp_f32_e32 v189, v189
	v_add_f32_dpp v180, v180, v180 row_ror:8 row_mask:0xf bank_mask:0xf
	v_exp_f32_e32 v190, v190
	v_exp_f32_e32 v191, v191
	v_mov_b32_e32 v181, v180
	v_pk_add_f32 v[188:189], v[188:189], v[10:11]
	v_pk_add_f32 v[190:191], v[190:191], v[10:11]
	v_permlane16_swap_b32_e32 v180, v181
	v_rcp_f32_e32 v188, v188
	v_rcp_f32_e32 v189, v189
	v_add_f32_e32 v180, v180, v181
	v_rcp_f32_e32 v190, v190
	v_rcp_f32_e32 v191, v191
	v_mov_b32_e32 v182, s21
	v_fmac_f32_e32 v182, s20, v180
	v_rsq_f32_e32 v182, v182
	v_pk_mul_f32 v[188:189], v[188:189], v[184:185]
	v_pk_mul_f32 v[190:191], v[190:191], v[186:187]
	v_mov_b32_e32 v183, v182
	v_pk_mul_f32 v[188:189], v[188:189], v[4:5]
	v_pk_mul_f32 v[190:191], v[190:191], v[6:7]
	v_pk_mul_f32 v[44:45], v[44:45], v[182:183]
	v_pk_mul_f32 v[46:47], v[46:47], v[182:183]
	v_pk_mul_f32 v[44:45], v[44:45], v[188:189]
	v_pk_mul_f32 v[46:47], v[46:47], v[190:191]
	v_cvt_pk_bf16_f32 v200, v44, v45
	v_cvt_pk_bf16_f32 v201, v46, v47
	global_store_dwordx2 v2, v[200:201], s[8:9]
	s_add_u32 s8, s8, 0x100000
	s_addc_u32 s9, s9, 0
	s_waitcnt vmcnt(27)
	v_pk_add_f32 v[48:49], v[48:49], v[112:113]
	v_pk_add_f32 v[50:51], v[50:51], v[114:115]
	v_mul_f32_e32 v180, v48, v48
	v_fmac_f32_e32 v180, v49, v49
	v_fmac_f32_e32 v180, v50, v50
	v_fmac_f32_e32 v180, v51, v51
	v_lshlrev_b32_e32 v184, 16, v160
	v_and_b32_e32 v185, 0xffff0000, v160
	v_add_f32_dpp v180, v180, v180 quad_perm:[1,0,3,2] row_mask:0xf bank_mask:0xf
	v_lshlrev_b32_e32 v186, 16, v161
	v_and_b32_e32 v187, 0xffff0000, v161
	v_add_f32_dpp v180, v180, v180 quad_perm:[2,3,0,1] row_mask:0xf bank_mask:0xf
	v_pk_mul_f32 v[188:189], v[184:185], v[8:9]
	v_pk_mul_f32 v[190:191], v[186:187], v[8:9]
	v_add_f32_dpp v180, v180, v180 row_ror:4 row_mask:0xf bank_mask:0xf
	v_exp_f32_e32 v188, v188
	v_exp_f32_e32 v189, v189
	v_add_f32_dpp v180, v180, v180 row_ror:8 row_mask:0xf bank_mask:0xf
	v_exp_f32_e32 v190, v190
	v_exp_f32_e32 v191, v191
	v_mov_b32_e32 v181, v180
	v_pk_add_f32 v[188:189], v[188:189], v[10:11]
	v_pk_add_f32 v[190:191], v[190:191], v[10:11]
	v_permlane16_swap_b32_e32 v180, v181
	v_rcp_f32_e32 v188, v188
	v_rcp_f32_e32 v189, v189
	v_add_f32_e32 v180, v180, v181
	v_rcp_f32_e32 v190, v190
	v_rcp_f32_e32 v191, v191
	v_mov_b32_e32 v182, s21
	v_fmac_f32_e32 v182, s20, v180
	v_rsq_f32_e32 v182, v182
	v_pk_mul_f32 v[188:189], v[188:189], v[184:185]
	v_pk_mul_f32 v[190:191], v[190:191], v[186:187]
	v_mov_b32_e32 v183, v182
	v_pk_mul_f32 v[188:189], v[188:189], v[4:5]
	v_pk_mul_f32 v[190:191], v[190:191], v[6:7]
	v_pk_mul_f32 v[48:49], v[48:49], v[182:183]
	v_pk_mul_f32 v[50:51], v[50:51], v[182:183]
	v_pk_mul_f32 v[48:49], v[48:49], v[188:189]
	v_pk_mul_f32 v[50:51], v[50:51], v[190:191]
	v_cvt_pk_bf16_f32 v202, v48, v49
	v_cvt_pk_bf16_f32 v203, v50, v51
	global_store_dwordx2 v2, v[202:203], s[8:9]
	s_add_u32 s8, s8, 0x100000
	s_addc_u32 s9, s9, 0
	s_waitcnt vmcnt(25)
	v_pk_add_f32 v[52:53], v[52:53], v[116:117]
	v_pk_add_f32 v[54:55], v[54:55], v[118:119]
	v_mul_f32_e32 v180, v52, v52
	v_fmac_f32_e32 v180, v53, v53
	v_fmac_f32_e32 v180, v54, v54
	v_fmac_f32_e32 v180, v55, v55
	v_lshlrev_b32_e32 v184, 16, v162
	v_and_b32_e32 v185, 0xffff0000, v162
	v_add_f32_dpp v180, v180, v180 quad_perm:[1,0,3,2] row_mask:0xf bank_mask:0xf
	v_lshlrev_b32_e32 v186, 16, v163
	v_and_b32_e32 v187, 0xffff0000, v163
	v_add_f32_dpp v180, v180, v180 quad_perm:[2,3,0,1] row_mask:0xf bank_mask:0xf
	v_pk_mul_f32 v[188:189], v[184:185], v[8:9]
	v_pk_mul_f32 v[190:191], v[186:187], v[8:9]
	v_add_f32_dpp v180, v180, v180 row_ror:4 row_mask:0xf bank_mask:0xf
	v_exp_f32_e32 v188, v188
	v_exp_f32_e32 v189, v189
	v_add_f32_dpp v180, v180, v180 row_ror:8 row_mask:0xf bank_mask:0xf
	v_exp_f32_e32 v190, v190
	v_exp_f32_e32 v191, v191
	v_mov_b32_e32 v181, v180
	v_pk_add_f32 v[188:189], v[188:189], v[10:11]
	v_pk_add_f32 v[190:191], v[190:191], v[10:11]
	v_permlane16_swap_b32_e32 v180, v181
	v_rcp_f32_e32 v188, v188
	v_rcp_f32_e32 v189, v189
	v_add_f32_e32 v180, v180, v181
	v_rcp_f32_e32 v190, v190
	v_rcp_f32_e32 v191, v191
	v_mov_b32_e32 v182, s21
	v_fmac_f32_e32 v182, s20, v180
	v_rsq_f32_e32 v182, v182
	v_pk_mul_f32 v[188:189], v[188:189], v[184:185]
	v_pk_mul_f32 v[190:191], v[190:191], v[186:187]
	v_mov_b32_e32 v183, v182
	v_pk_mul_f32 v[188:189], v[188:189], v[4:5]
	v_pk_mul_f32 v[190:191], v[190:191], v[6:7]
	v_pk_mul_f32 v[52:53], v[52:53], v[182:183]
	v_pk_mul_f32 v[54:55], v[54:55], v[182:183]
	v_pk_mul_f32 v[52:53], v[52:53], v[188:189]
	v_pk_mul_f32 v[54:55], v[54:55], v[190:191]
	v_cvt_pk_bf16_f32 v204, v52, v53
	v_cvt_pk_bf16_f32 v205, v54, v55
	global_store_dwordx2 v2, v[204:205], s[8:9]
	s_add_u32 s8, s8, 0x100000
	s_addc_u32 s9, s9, 0
	s_waitcnt vmcnt(23)
	v_pk_add_f32 v[56:57], v[56:57], v[120:121]
	v_pk_add_f32 v[58:59], v[58:59], v[122:123]
	v_mul_f32_e32 v180, v56, v56
	v_fmac_f32_e32 v180, v57, v57
	v_fmac_f32_e32 v180, v58, v58
	v_fmac_f32_e32 v180, v59, v59
	v_lshlrev_b32_e32 v184, 16, v164
	v_and_b32_e32 v185, 0xffff0000, v164
	v_add_f32_dpp v180, v180, v180 quad_perm:[1,0,3,2] row_mask:0xf bank_mask:0xf
	v_lshlrev_b32_e32 v186, 16, v165
	v_and_b32_e32 v187, 0xffff0000, v165
	v_add_f32_dpp v180, v180, v180 quad_perm:[2,3,0,1] row_mask:0xf bank_mask:0xf
	v_pk_mul_f32 v[188:189], v[184:185], v[8:9]
	v_pk_mul_f32 v[190:191], v[186:187], v[8:9]
	v_add_f32_dpp v180, v180, v180 row_ror:4 row_mask:0xf bank_mask:0xf
	v_exp_f32_e32 v188, v188
	v_exp_f32_e32 v189, v189
	v_add_f32_dpp v180, v180, v180 row_ror:8 row_mask:0xf bank_mask:0xf
	v_exp_f32_e32 v190, v190
	v_exp_f32_e32 v191, v191
	v_mov_b32_e32 v181, v180
	v_pk_add_f32 v[188:189], v[188:189], v[10:11]
	v_pk_add_f32 v[190:191], v[190:191], v[10:11]
	v_permlane16_swap_b32_e32 v180, v181
	v_rcp_f32_e32 v188, v188
	v_rcp_f32_e32 v189, v189
	v_add_f32_e32 v180, v180, v181
	v_rcp_f32_e32 v190, v190
	v_rcp_f32_e32 v191, v191
	v_mov_b32_e32 v182, s21
	v_fmac_f32_e32 v182, s20, v180
	v_rsq_f32_e32 v182, v182
	v_pk_mul_f32 v[188:189], v[188:189], v[184:185]
	v_pk_mul_f32 v[190:191], v[190:191], v[186:187]
	v_mov_b32_e32 v183, v182
	v_pk_mul_f32 v[188:189], v[188:189], v[4:5]
	v_pk_mul_f32 v[190:191], v[190:191], v[6:7]
	v_pk_mul_f32 v[56:57], v[56:57], v[182:183]
	v_pk_mul_f32 v[58:59], v[58:59], v[182:183]
	v_pk_mul_f32 v[56:57], v[56:57], v[188:189]
	v_pk_mul_f32 v[58:59], v[58:59], v[190:191]
	v_cvt_pk_bf16_f32 v206, v56, v57
	v_cvt_pk_bf16_f32 v207, v58, v59
	global_store_dwordx2 v2, v[206:207], s[8:9]
	s_add_u32 s8, s8, 0x100000
	s_addc_u32 s9, s9, 0
	s_waitcnt vmcnt(21)
	v_pk_add_f32 v[60:61], v[60:61], v[124:125]
	v_pk_add_f32 v[62:63], v[62:63], v[126:127]
	v_mul_f32_e32 v180, v60, v60
	v_fmac_f32_e32 v180, v61, v61
	v_fmac_f32_e32 v180, v62, v62
	v_fmac_f32_e32 v180, v63, v63
	v_lshlrev_b32_e32 v184, 16, v166
	v_and_b32_e32 v185, 0xffff0000, v166
	v_add_f32_dpp v180, v180, v180 quad_perm:[1,0,3,2] row_mask:0xf bank_mask:0xf
	v_lshlrev_b32_e32 v186, 16, v167
	v_and_b32_e32 v187, 0xffff0000, v167
	v_add_f32_dpp v180, v180, v180 quad_perm:[2,3,0,1] row_mask:0xf bank_mask:0xf
	v_pk_mul_f32 v[188:189], v[184:185], v[8:9]
	v_pk_mul_f32 v[190:191], v[186:187], v[8:9]
	v_add_f32_dpp v180, v180, v180 row_ror:4 row_mask:0xf bank_mask:0xf
	v_exp_f32_e32 v188, v188
	v_exp_f32_e32 v189, v189
	v_add_f32_dpp v180, v180, v180 row_ror:8 row_mask:0xf bank_mask:0xf
	v_exp_f32_e32 v190, v190
	v_exp_f32_e32 v191, v191
	v_mov_b32_e32 v181, v180
	v_pk_add_f32 v[188:189], v[188:189], v[10:11]
	v_pk_add_f32 v[190:191], v[190:191], v[10:11]
	v_permlane16_swap_b32_e32 v180, v181
	v_rcp_f32_e32 v188, v188
	v_rcp_f32_e32 v189, v189
	v_add_f32_e32 v180, v180, v181
	v_rcp_f32_e32 v190, v190
	v_rcp_f32_e32 v191, v191
	v_mov_b32_e32 v182, s21
	v_fmac_f32_e32 v182, s20, v180
	v_rsq_f32_e32 v182, v182
	v_pk_mul_f32 v[188:189], v[188:189], v[184:185]
	v_pk_mul_f32 v[190:191], v[190:191], v[186:187]
	v_mov_b32_e32 v183, v182
	v_pk_mul_f32 v[188:189], v[188:189], v[4:5]
	v_pk_mul_f32 v[190:191], v[190:191], v[6:7]
	v_pk_mul_f32 v[60:61], v[60:61], v[182:183]
	v_pk_mul_f32 v[62:63], v[62:63], v[182:183]
	v_pk_mul_f32 v[60:61], v[60:61], v[188:189]
	v_pk_mul_f32 v[62:63], v[62:63], v[190:191]
	v_cvt_pk_bf16_f32 v200, v60, v61
	v_cvt_pk_bf16_f32 v201, v62, v63
	global_store_dwordx2 v2, v[200:201], s[8:9]
	s_add_u32 s8, s8, 0x100000
	s_addc_u32 s9, s9, 0
	s_waitcnt vmcnt(19)
	v_pk_add_f32 v[64:65], v[64:65], v[128:129]
	v_pk_add_f32 v[66:67], v[66:67], v[130:131]
	v_mul_f32_e32 v180, v64, v64
	v_fmac_f32_e32 v180, v65, v65
	v_fmac_f32_e32 v180, v66, v66
	v_fmac_f32_e32 v180, v67, v67
	v_lshlrev_b32_e32 v184, 16, v168
	v_and_b32_e32 v185, 0xffff0000, v168
	v_add_f32_dpp v180, v180, v180 quad_perm:[1,0,3,2] row_mask:0xf bank_mask:0xf
	v_lshlrev_b32_e32 v186, 16, v169
	v_and_b32_e32 v187, 0xffff0000, v169
	v_add_f32_dpp v180, v180, v180 quad_perm:[2,3,0,1] row_mask:0xf bank_mask:0xf
	v_pk_mul_f32 v[188:189], v[184:185], v[8:9]
	v_pk_mul_f32 v[190:191], v[186:187], v[8:9]
	v_add_f32_dpp v180, v180, v180 row_ror:4 row_mask:0xf bank_mask:0xf
	v_exp_f32_e32 v188, v188
	v_exp_f32_e32 v189, v189
	v_add_f32_dpp v180, v180, v180 row_ror:8 row_mask:0xf bank_mask:0xf
	v_exp_f32_e32 v190, v190
	v_exp_f32_e32 v191, v191
	v_mov_b32_e32 v181, v180
	v_pk_add_f32 v[188:189], v[188:189], v[10:11]
	v_pk_add_f32 v[190:191], v[190:191], v[10:11]
	v_permlane16_swap_b32_e32 v180, v181
	v_rcp_f32_e32 v188, v188
	v_rcp_f32_e32 v189, v189
	v_add_f32_e32 v180, v180, v181
	v_rcp_f32_e32 v190, v190
	v_rcp_f32_e32 v191, v191
	v_mov_b32_e32 v182, s21
	v_fmac_f32_e32 v182, s20, v180
	v_rsq_f32_e32 v182, v182
	v_pk_mul_f32 v[188:189], v[188:189], v[184:185]
	v_pk_mul_f32 v[190:191], v[190:191], v[186:187]
	v_mov_b32_e32 v183, v182
	v_pk_mul_f32 v[188:189], v[188:189], v[4:5]
	v_pk_mul_f32 v[190:191], v[190:191], v[6:7]
	v_pk_mul_f32 v[64:65], v[64:65], v[182:183]
	v_pk_mul_f32 v[66:67], v[66:67], v[182:183]
	v_pk_mul_f32 v[64:65], v[64:65], v[188:189]
	v_pk_mul_f32 v[66:67], v[66:67], v[190:191]
	v_cvt_pk_bf16_f32 v202, v64, v65
	v_cvt_pk_bf16_f32 v203, v66, v67
	global_store_dwordx2 v2, v[202:203], s[8:9]
	s_add_u32 s8, s8, 0x100000
	s_addc_u32 s9, s9, 0
	s_waitcnt vmcnt(17)
	v_pk_add_f32 v[68:69], v[68:69], v[132:133]
	v_pk_add_f32 v[70:71], v[70:71], v[134:135]
	v_mul_f32_e32 v180, v68, v68
	v_fmac_f32_e32 v180, v69, v69
	v_fmac_f32_e32 v180, v70, v70
	v_fmac_f32_e32 v180, v71, v71
	v_lshlrev_b32_e32 v184, 16, v170
	v_and_b32_e32 v185, 0xffff0000, v170
	v_add_f32_dpp v180, v180, v180 quad_perm:[1,0,3,2] row_mask:0xf bank_mask:0xf
	v_lshlrev_b32_e32 v186, 16, v171
	v_and_b32_e32 v187, 0xffff0000, v171
	v_add_f32_dpp v180, v180, v180 quad_perm:[2,3,0,1] row_mask:0xf bank_mask:0xf
	v_pk_mul_f32 v[188:189], v[184:185], v[8:9]
	v_pk_mul_f32 v[190:191], v[186:187], v[8:9]
	v_add_f32_dpp v180, v180, v180 row_ror:4 row_mask:0xf bank_mask:0xf
	v_exp_f32_e32 v188, v188
	v_exp_f32_e32 v189, v189
	v_add_f32_dpp v180, v180, v180 row_ror:8 row_mask:0xf bank_mask:0xf
	v_exp_f32_e32 v190, v190
	v_exp_f32_e32 v191, v191
	v_mov_b32_e32 v181, v180
	v_pk_add_f32 v[188:189], v[188:189], v[10:11]
	v_pk_add_f32 v[190:191], v[190:191], v[10:11]
	v_permlane16_swap_b32_e32 v180, v181
	v_rcp_f32_e32 v188, v188
	v_rcp_f32_e32 v189, v189
	v_add_f32_e32 v180, v180, v181
	v_rcp_f32_e32 v190, v190
	v_rcp_f32_e32 v191, v191
	v_mov_b32_e32 v182, s21
	v_fmac_f32_e32 v182, s20, v180
	v_rsq_f32_e32 v182, v182
	v_pk_mul_f32 v[188:189], v[188:189], v[184:185]
	v_pk_mul_f32 v[190:191], v[190:191], v[186:187]
	v_mov_b32_e32 v183, v182
	v_pk_mul_f32 v[188:189], v[188:189], v[4:5]
	v_pk_mul_f32 v[190:191], v[190:191], v[6:7]
	v_pk_mul_f32 v[68:69], v[68:69], v[182:183]
	v_pk_mul_f32 v[70:71], v[70:71], v[182:183]
	v_pk_mul_f32 v[68:69], v[68:69], v[188:189]
	v_pk_mul_f32 v[70:71], v[70:71], v[190:191]
	v_cvt_pk_bf16_f32 v204, v68, v69
	v_cvt_pk_bf16_f32 v205, v70, v71
	global_store_dwordx2 v2, v[204:205], s[8:9]
	s_add_u32 s8, s8, 0x100000
	s_addc_u32 s9, s9, 0
	s_waitcnt vmcnt(15)
	v_pk_add_f32 v[72:73], v[72:73], v[136:137]
	v_pk_add_f32 v[74:75], v[74:75], v[138:139]
	v_mul_f32_e32 v180, v72, v72
	v_fmac_f32_e32 v180, v73, v73
	v_fmac_f32_e32 v180, v74, v74
	v_fmac_f32_e32 v180, v75, v75
	v_lshlrev_b32_e32 v184, 16, v172
	v_and_b32_e32 v185, 0xffff0000, v172
	v_add_f32_dpp v180, v180, v180 quad_perm:[1,0,3,2] row_mask:0xf bank_mask:0xf
	v_lshlrev_b32_e32 v186, 16, v173
	v_and_b32_e32 v187, 0xffff0000, v173
	v_add_f32_dpp v180, v180, v180 quad_perm:[2,3,0,1] row_mask:0xf bank_mask:0xf
	v_pk_mul_f32 v[188:189], v[184:185], v[8:9]
	v_pk_mul_f32 v[190:191], v[186:187], v[8:9]
	v_add_f32_dpp v180, v180, v180 row_ror:4 row_mask:0xf bank_mask:0xf
	v_exp_f32_e32 v188, v188
	v_exp_f32_e32 v189, v189
	v_add_f32_dpp v180, v180, v180 row_ror:8 row_mask:0xf bank_mask:0xf
	v_exp_f32_e32 v190, v190
	v_exp_f32_e32 v191, v191
	v_mov_b32_e32 v181, v180
	v_pk_add_f32 v[188:189], v[188:189], v[10:11]
	v_pk_add_f32 v[190:191], v[190:191], v[10:11]
	v_permlane16_swap_b32_e32 v180, v181
	v_rcp_f32_e32 v188, v188
	v_rcp_f32_e32 v189, v189
	v_add_f32_e32 v180, v180, v181
	v_rcp_f32_e32 v190, v190
	v_rcp_f32_e32 v191, v191
	v_mov_b32_e32 v182, s21
	v_fmac_f32_e32 v182, s20, v180
	v_rsq_f32_e32 v182, v182
	v_pk_mul_f32 v[188:189], v[188:189], v[184:185]
	v_pk_mul_f32 v[190:191], v[190:191], v[186:187]
	v_mov_b32_e32 v183, v182
	v_pk_mul_f32 v[188:189], v[188:189], v[4:5]
	v_pk_mul_f32 v[190:191], v[190:191], v[6:7]
	v_pk_mul_f32 v[72:73], v[72:73], v[182:183]
	v_pk_mul_f32 v[74:75], v[74:75], v[182:183]
	v_pk_mul_f32 v[72:73], v[72:73], v[188:189]
	v_pk_mul_f32 v[74:75], v[74:75], v[190:191]
	v_cvt_pk_bf16_f32 v206, v72, v73
	v_cvt_pk_bf16_f32 v207, v74, v75
	global_store_dwordx2 v2, v[206:207], s[8:9]
	s_waitcnt vmcnt(0)
	s_branch .LBB0_2045
